# phase 1: pre-norm body hand-scheduled (batched parameter loads, nt on x), Wf fold on f32 MFMA 32x32x2 (no LDS); phase 0 ada/mcs 64 loads in flight; grid barrier waiters poll TOPGEN
# speedup vs baseline: 1.0947x; 1.0303x over previous
.LBB0_74:
	s_andn2_b64 vcc, exec, s[4:5]
	s_cbranch_vccnz .LBB0_78
	s_lshl_b32 s4, s51, 6
	s_load_dwordx2 s[82:83], s[8:9], 0x68
	s_and_b32 s12, s4, 0xffffc000
	s_lshl_b32 s4, s52, 2
	s_and_b32 s4, s4, 0x300
	v_lshl_or_b32 v128, v130, 2, s4
	s_lshr_b32 s80, s51, 2
	s_load_dwordx2 s[4:5], s[8:9], 0xa8
	s_lshl_b64 s[6:7], s[12:13], 2
	s_and_b32 s80, s80, 63
	v_mul_u32_u24_e32 v4, s80, v130
	v_mov_b32_e32 v0, 0
	v_and_b32_e32 v4, 63, v4
	v_mov_b32_e32 v1, v0
	v_lshlrev_b32_e32 v4, 8, v4
	ds_read_b64 v[100:101], v4
	s_waitcnt lgkmcnt(0)
	s_add_u32 s6, s82, s6
	s_addc_u32 s7, s83, s7
	global_load_dword v36, v128, s[6:7]
	global_load_dword v37, v128, s[6:7] offset:1024
	global_load_dword v38, v128, s[6:7] offset:2048
	global_load_dword v39, v128, s[6:7] offset:3072
	s_add_u32 s6, s6, 0x1000
	s_addc_u32 s7, s7, 0
	global_load_dword v40, v128, s[6:7]
	global_load_dword v41, v128, s[6:7] offset:1024
	global_load_dword v42, v128, s[6:7] offset:2048
	global_load_dword v43, v128, s[6:7] offset:3072
	s_add_u32 s6, s6, 0x1000
	s_addc_u32 s7, s7, 0
	global_load_dword v44, v128, s[6:7]
	global_load_dword v45, v128, s[6:7] offset:1024
	global_load_dword v46, v128, s[6:7] offset:2048
	global_load_dword v47, v128, s[6:7] offset:3072
	s_add_u32 s6, s6, 0x1000
	s_addc_u32 s7, s7, 0
	global_load_dword v48, v128, s[6:7]
	global_load_dword v49, v128, s[6:7] offset:1024
	global_load_dword v50, v128, s[6:7] offset:2048
	global_load_dword v51, v128, s[6:7] offset:3072
	s_add_u32 s6, s6, 0x1000
	s_addc_u32 s7, s7, 0
	global_load_dword v52, v128, s[6:7]
	global_load_dword v53, v128, s[6:7] offset:1024
	global_load_dword v54, v128, s[6:7] offset:2048
	global_load_dword v55, v128, s[6:7] offset:3072
	s_add_u32 s6, s6, 0x1000
	s_addc_u32 s7, s7, 0
	global_load_dword v56, v128, s[6:7]
	global_load_dword v57, v128, s[6:7] offset:1024
	global_load_dword v58, v128, s[6:7] offset:2048
	global_load_dword v59, v128, s[6:7] offset:3072
	s_add_u32 s6, s6, 0x1000
	s_addc_u32 s7, s7, 0
	global_load_dword v60, v128, s[6:7]
	global_load_dword v61, v128, s[6:7] offset:1024
	global_load_dword v62, v128, s[6:7] offset:2048
	global_load_dword v63, v128, s[6:7] offset:3072
	s_add_u32 s6, s6, 0x1000
	s_addc_u32 s7, s7, 0
	global_load_dword v64, v128, s[6:7]
	global_load_dword v65, v128, s[6:7] offset:1024
	global_load_dword v66, v128, s[6:7] offset:2048
	global_load_dword v67, v128, s[6:7] offset:3072
	s_add_u32 s6, s6, 0x1000
	s_addc_u32 s7, s7, 0
	global_load_dword v68, v128, s[6:7]
	global_load_dword v69, v128, s[6:7] offset:1024
	global_load_dword v70, v128, s[6:7] offset:2048
	global_load_dword v71, v128, s[6:7] offset:3072
	s_add_u32 s6, s6, 0x1000
	s_addc_u32 s7, s7, 0
	global_load_dword v72, v128, s[6:7]
	global_load_dword v73, v128, s[6:7] offset:1024
	global_load_dword v74, v128, s[6:7] offset:2048
	global_load_dword v75, v128, s[6:7] offset:3072
	s_add_u32 s6, s6, 0x1000
	s_addc_u32 s7, s7, 0
	global_load_dword v76, v128, s[6:7]
	global_load_dword v77, v128, s[6:7] offset:1024
	global_load_dword v78, v128, s[6:7] offset:2048
	global_load_dword v79, v128, s[6:7] offset:3072
	s_add_u32 s6, s6, 0x1000
	s_addc_u32 s7, s7, 0
	global_load_dword v80, v128, s[6:7]
	global_load_dword v81, v128, s[6:7] offset:1024
	global_load_dword v82, v128, s[6:7] offset:2048
	global_load_dword v83, v128, s[6:7] offset:3072
	s_add_u32 s6, s6, 0x1000
	s_addc_u32 s7, s7, 0
	global_load_dword v84, v128, s[6:7]
	global_load_dword v85, v128, s[6:7] offset:1024
	global_load_dword v86, v128, s[6:7] offset:2048
	global_load_dword v87, v128, s[6:7] offset:3072
	s_add_u32 s6, s6, 0x1000
	s_addc_u32 s7, s7, 0
	global_load_dword v88, v128, s[6:7]
	global_load_dword v89, v128, s[6:7] offset:1024
	global_load_dword v90, v128, s[6:7] offset:2048
	global_load_dword v91, v128, s[6:7] offset:3072
	s_add_u32 s6, s6, 0x1000
	s_addc_u32 s7, s7, 0
	global_load_dword v92, v128, s[6:7]
	global_load_dword v93, v128, s[6:7] offset:1024
	global_load_dword v94, v128, s[6:7] offset:2048
	global_load_dword v95, v128, s[6:7] offset:3072
	s_add_u32 s6, s6, 0x1000
	s_addc_u32 s7, s7, 0
	global_load_dword v96, v128, s[6:7]
	global_load_dword v97, v128, s[6:7] offset:1024
	global_load_dword v98, v128, s[6:7] offset:2048
	global_load_dword v99, v128, s[6:7] offset:3072
	v_readlane_b32 s82, v100, 0
	v_readlane_b32 s83, v100, 1
	v_readlane_b32 s84, v100, 2
	v_readlane_b32 s85, v100, 3
	v_readlane_b32 s86, v100, 4
	v_readlane_b32 s87, v100, 5
	v_readlane_b32 s88, v100, 6
	v_readlane_b32 s89, v100, 7
	v_readlane_b32 s42, v101, 0
	v_readlane_b32 s43, v101, 1
	v_readlane_b32 s44, v101, 2
	v_readlane_b32 s45, v101, 3
	v_readlane_b32 s78, v101, 4
	v_readlane_b32 s79, v101, 5
	v_readlane_b32 s80, v101, 6
	v_readlane_b32 s81, v101, 7
	s_waitcnt vmcnt(56)
	v_fmac_f32_e32 v0, s82, v36
	v_fmac_f32_e32 v1, s42, v36
	v_fmac_f32_e32 v0, s83, v37
	v_fmac_f32_e32 v1, s43, v37
	v_fmac_f32_e32 v0, s84, v38
	v_fmac_f32_e32 v1, s44, v38
	v_fmac_f32_e32 v0, s85, v39
	v_fmac_f32_e32 v1, s45, v39
	v_fmac_f32_e32 v0, s86, v40
	v_fmac_f32_e32 v1, s78, v40
	v_fmac_f32_e32 v0, s87, v41
	v_fmac_f32_e32 v1, s79, v41
	v_fmac_f32_e32 v0, s88, v42
	v_fmac_f32_e32 v1, s80, v42
	v_fmac_f32_e32 v0, s89, v43
	v_fmac_f32_e32 v1, s81, v43
	v_readlane_b32 s82, v100, 8
	v_readlane_b32 s83, v100, 9
	v_readlane_b32 s84, v100, 10
	v_readlane_b32 s85, v100, 11
	v_readlane_b32 s86, v100, 12
	v_readlane_b32 s87, v100, 13
	v_readlane_b32 s88, v100, 14
	v_readlane_b32 s89, v100, 15
	v_readlane_b32 s42, v101, 8
	v_readlane_b32 s43, v101, 9
	v_readlane_b32 s44, v101, 10
	v_readlane_b32 s45, v101, 11
	v_readlane_b32 s78, v101, 12
	v_readlane_b32 s79, v101, 13
	v_readlane_b32 s80, v101, 14
	v_readlane_b32 s81, v101, 15
	s_waitcnt vmcnt(48)
	v_fmac_f32_e32 v0, s82, v44
	v_fmac_f32_e32 v1, s42, v44
	v_fmac_f32_e32 v0, s83, v45
	v_fmac_f32_e32 v1, s43, v45
	v_fmac_f32_e32 v0, s84, v46
	v_fmac_f32_e32 v1, s44, v46
	v_fmac_f32_e32 v0, s85, v47
	v_fmac_f32_e32 v1, s45, v47
	v_fmac_f32_e32 v0, s86, v48
	v_fmac_f32_e32 v1, s78, v48
	v_fmac_f32_e32 v0, s87, v49
	v_fmac_f32_e32 v1, s79, v49
	v_fmac_f32_e32 v0, s88, v50
	v_fmac_f32_e32 v1, s80, v50
	v_fmac_f32_e32 v0, s89, v51
	v_fmac_f32_e32 v1, s81, v51
	v_readlane_b32 s82, v100, 16
	v_readlane_b32 s83, v100, 17
	v_readlane_b32 s84, v100, 18
	v_readlane_b32 s85, v100, 19
	v_readlane_b32 s86, v100, 20
	v_readlane_b32 s87, v100, 21
	v_readlane_b32 s88, v100, 22
	v_readlane_b32 s89, v100, 23
	v_readlane_b32 s42, v101, 16
	v_readlane_b32 s43, v101, 17
	v_readlane_b32 s44, v101, 18
	v_readlane_b32 s45, v101, 19
	v_readlane_b32 s78, v101, 20
	v_readlane_b32 s79, v101, 21
	v_readlane_b32 s80, v101, 22
	v_readlane_b32 s81, v101, 23
	s_waitcnt vmcnt(40)
	v_fmac_f32_e32 v0, s82, v52
	v_fmac_f32_e32 v1, s42, v52
	v_fmac_f32_e32 v0, s83, v53
	v_fmac_f32_e32 v1, s43, v53
	v_fmac_f32_e32 v0, s84, v54
	v_fmac_f32_e32 v1, s44, v54
	v_fmac_f32_e32 v0, s85, v55
	v_fmac_f32_e32 v1, s45, v55
	v_fmac_f32_e32 v0, s86, v56
	v_fmac_f32_e32 v1, s78, v56
	v_fmac_f32_e32 v0, s87, v57
	v_fmac_f32_e32 v1, s79, v57
	v_fmac_f32_e32 v0, s88, v58
	v_fmac_f32_e32 v1, s80, v58
	v_fmac_f32_e32 v0, s89, v59
	v_fmac_f32_e32 v1, s81, v59
	v_readlane_b32 s82, v100, 24
	v_readlane_b32 s83, v100, 25
	v_readlane_b32 s84, v100, 26
	v_readlane_b32 s85, v100, 27
	v_readlane_b32 s86, v100, 28
	v_readlane_b32 s87, v100, 29
	v_readlane_b32 s88, v100, 30
	v_readlane_b32 s89, v100, 31
	v_readlane_b32 s42, v101, 24
	v_readlane_b32 s43, v101, 25
	v_readlane_b32 s44, v101, 26
	v_readlane_b32 s45, v101, 27
	v_readlane_b32 s78, v101, 28
	v_readlane_b32 s79, v101, 29
	v_readlane_b32 s80, v101, 30
	v_readlane_b32 s81, v101, 31
	s_waitcnt vmcnt(32)
	v_fmac_f32_e32 v0, s82, v60
	v_fmac_f32_e32 v1, s42, v60
	v_fmac_f32_e32 v0, s83, v61
	v_fmac_f32_e32 v1, s43, v61
	v_fmac_f32_e32 v0, s84, v62
	v_fmac_f32_e32 v1, s44, v62
	v_fmac_f32_e32 v0, s85, v63
	v_fmac_f32_e32 v1, s45, v63
	v_fmac_f32_e32 v0, s86, v64
	v_fmac_f32_e32 v1, s78, v64
	v_fmac_f32_e32 v0, s87, v65
	v_fmac_f32_e32 v1, s79, v65
	v_fmac_f32_e32 v0, s88, v66
	v_fmac_f32_e32 v1, s80, v66
	v_fmac_f32_e32 v0, s89, v67
	v_fmac_f32_e32 v1, s81, v67
	v_readlane_b32 s82, v100, 32
	v_readlane_b32 s83, v100, 33
	v_readlane_b32 s84, v100, 34
	v_readlane_b32 s85, v100, 35
	v_readlane_b32 s86, v100, 36
	v_readlane_b32 s87, v100, 37
	v_readlane_b32 s88, v100, 38
	v_readlane_b32 s89, v100, 39
	v_readlane_b32 s42, v101, 32
	v_readlane_b32 s43, v101, 33
	v_readlane_b32 s44, v101, 34
	v_readlane_b32 s45, v101, 35
	v_readlane_b32 s78, v101, 36
	v_readlane_b32 s79, v101, 37
	v_readlane_b32 s80, v101, 38
	v_readlane_b32 s81, v101, 39
	s_waitcnt vmcnt(24)
	v_fmac_f32_e32 v0, s82, v68
	v_fmac_f32_e32 v1, s42, v68
	v_fmac_f32_e32 v0, s83, v69
	v_fmac_f32_e32 v1, s43, v69
	v_fmac_f32_e32 v0, s84, v70
	v_fmac_f32_e32 v1, s44, v70
	v_fmac_f32_e32 v0, s85, v71
	v_fmac_f32_e32 v1, s45, v71
	v_fmac_f32_e32 v0, s86, v72
	v_fmac_f32_e32 v1, s78, v72
	v_fmac_f32_e32 v0, s87, v73
	v_fmac_f32_e32 v1, s79, v73
	v_fmac_f32_e32 v0, s88, v74
	v_fmac_f32_e32 v1, s80, v74
	v_fmac_f32_e32 v0, s89, v75
	v_fmac_f32_e32 v1, s81, v75
	v_readlane_b32 s82, v100, 40
	v_readlane_b32 s83, v100, 41
	v_readlane_b32 s84, v100, 42
	v_readlane_b32 s85, v100, 43
	v_readlane_b32 s86, v100, 44
	v_readlane_b32 s87, v100, 45
	v_readlane_b32 s88, v100, 46
	v_readlane_b32 s89, v100, 47
	v_readlane_b32 s42, v101, 40
	v_readlane_b32 s43, v101, 41
	v_readlane_b32 s44, v101, 42
	v_readlane_b32 s45, v101, 43
	v_readlane_b32 s78, v101, 44
	v_readlane_b32 s79, v101, 45
	v_readlane_b32 s80, v101, 46
	v_readlane_b32 s81, v101, 47
	s_waitcnt vmcnt(16)
	v_fmac_f32_e32 v0, s82, v76
	v_fmac_f32_e32 v1, s42, v76
	v_fmac_f32_e32 v0, s83, v77
	v_fmac_f32_e32 v1, s43, v77
	v_fmac_f32_e32 v0, s84, v78
	v_fmac_f32_e32 v1, s44, v78
	v_fmac_f32_e32 v0, s85, v79
	v_fmac_f32_e32 v1, s45, v79
	v_fmac_f32_e32 v0, s86, v80
	v_fmac_f32_e32 v1, s78, v80
	v_fmac_f32_e32 v0, s87, v81
	v_fmac_f32_e32 v1, s79, v81
	v_fmac_f32_e32 v0, s88, v82
	v_fmac_f32_e32 v1, s80, v82
	v_fmac_f32_e32 v0, s89, v83
	v_fmac_f32_e32 v1, s81, v83
	v_readlane_b32 s82, v100, 48
	v_readlane_b32 s83, v100, 49
	v_readlane_b32 s84, v100, 50
	v_readlane_b32 s85, v100, 51
	v_readlane_b32 s86, v100, 52
	v_readlane_b32 s87, v100, 53
	v_readlane_b32 s88, v100, 54
	v_readlane_b32 s89, v100, 55
	v_readlane_b32 s42, v101, 48
	v_readlane_b32 s43, v101, 49
	v_readlane_b32 s44, v101, 50
	v_readlane_b32 s45, v101, 51
	v_readlane_b32 s78, v101, 52
	v_readlane_b32 s79, v101, 53
	v_readlane_b32 s80, v101, 54
	v_readlane_b32 s81, v101, 55
	s_waitcnt vmcnt(8)
	v_fmac_f32_e32 v0, s82, v84
	v_fmac_f32_e32 v1, s42, v84
	v_fmac_f32_e32 v0, s83, v85
	v_fmac_f32_e32 v1, s43, v85
	v_fmac_f32_e32 v0, s84, v86
	v_fmac_f32_e32 v1, s44, v86
	v_fmac_f32_e32 v0, s85, v87
	v_fmac_f32_e32 v1, s45, v87
	v_fmac_f32_e32 v0, s86, v88
	v_fmac_f32_e32 v1, s78, v88
	v_fmac_f32_e32 v0, s87, v89
	v_fmac_f32_e32 v1, s79, v89
	v_fmac_f32_e32 v0, s88, v90
	v_fmac_f32_e32 v1, s80, v90
	v_fmac_f32_e32 v0, s89, v91
	v_fmac_f32_e32 v1, s81, v91
	v_readlane_b32 s82, v100, 56
	v_readlane_b32 s83, v100, 57
	v_readlane_b32 s84, v100, 58
	v_readlane_b32 s85, v100, 59
	v_readlane_b32 s86, v100, 60
	v_readlane_b32 s87, v100, 61
	v_readlane_b32 s88, v100, 62
	v_readlane_b32 s89, v100, 63
	v_readlane_b32 s42, v101, 56
	v_readlane_b32 s43, v101, 57
	v_readlane_b32 s44, v101, 58
	v_readlane_b32 s45, v101, 59
	v_readlane_b32 s78, v101, 60
	v_readlane_b32 s79, v101, 61
	v_readlane_b32 s80, v101, 62
	v_readlane_b32 s81, v101, 63
	s_waitcnt vmcnt(0)
	v_fmac_f32_e32 v0, s82, v92
	v_fmac_f32_e32 v1, s42, v92
	v_fmac_f32_e32 v0, s83, v93
	v_fmac_f32_e32 v1, s43, v93
	v_fmac_f32_e32 v0, s84, v94
	v_fmac_f32_e32 v1, s44, v94
	v_fmac_f32_e32 v0, s85, v95
	v_fmac_f32_e32 v1, s45, v95
	v_fmac_f32_e32 v0, s86, v96
	v_fmac_f32_e32 v1, s78, v96
	v_fmac_f32_e32 v0, s87, v97
	v_fmac_f32_e32 v1, s79, v97
	v_fmac_f32_e32 v0, s88, v98
	v_fmac_f32_e32 v1, s80, v98
	v_fmac_f32_e32 v0, s89, v99
	v_fmac_f32_e32 v1, s81, v99
	s_add_i32 s6, s17, 0xfffff600
	s_lshl_b32 s7, s6, 6
	s_and_b32 s12, s7, 0xc0
	v_or_b32_e32 v4, s12, v130
	s_and_b32 s12, s7, 0xfffeff00
	s_add_u32 s4, s4, 0x1fe000
	s_addc_u32 s5, s5, 0
	s_lshl_b32 s6, s6, 7
	s_and_b32 s6, s6, 0xfffe0000
	s_and_b32 s7, s7, 0xff00
	s_or_b32 s7, s7, s6
	v_or_b32_e32 v128, s7, v4
	v_lshl_add_u64 v[2:3], v[128:129], 2, s[4:5]
	s_or_b32 s6, s12, s6
	global_store_dword v[2:3], v0, off
	v_or_b32_e32 v0, s6, v4
	v_or_b32_e32 v128, 0x10000, v0
	v_lshl_add_u64 v[2:3], v[128:129], 2, s[4:5]
	global_store_dword v[2:3], v1, off

.LBB0_84:
	s_andn2_b64 vcc, exec, s[4:5]
	s_cbranch_vccnz .LBB0_24
	s_and_b32 s4, s17, 0xffff
	s_mul_i32 s12, s4, 0xaaab
	s_load_dwordx4 s[4:7], s[8:9], 0x20
	s_load_dwordx2 s[78:79], s[8:9], 0x38
	s_bfe_u32 s44, s12, 0x40015
	s_lshl_b32 s80, s44, 6
	v_or_b32_e32 v0, s80, v130
	v_lshlrev_b32_e32 v128, 2, v0
	s_waitcnt lgkmcnt(0)
	v_lshl_add_u64 v[0:1], s[4:5], 0, v[128:129]
	v_add_co_u32_e32 v2, vcc, s55, v0
	v_lshl_add_u64 v[4:5], s[78:79], 0, v[134:135]
	s_nop 0
	v_addc_co_u32_e32 v3, vcc, 0, v1, vcc
	v_add_co_u32_e32 v0, vcc, s56, v0
	global_load_dword v6, v128, s[6:7]
	global_load_dword v7, v128, s[4:5]
	global_load_dword v8, v[2:3], off offset:-4096
	global_load_dword v9, v[2:3], off
	v_addc_co_u32_e32 v1, vcc, 0, v1, vcc
	global_load_dword v14, v[0:1], off
	s_lshr_b32 s4, s12, 21
	s_mul_i32 s4, s4, 48
	s_sub_i32 s12, s17, s4
	s_cmpk_gt_u32 s17, 0x2ff
	s_cselect_b64 s[6:7], -1, 0
	s_and_b64 s[4:5], s[6:7], exec
	s_load_dwordx2 s[42:43], s[8:9], 0xa8
	s_cselect_b32 s4, 0x400, 0
	s_lshl_b32 s5, s12, 6
	s_lshl_b32 s12, s12, 8
	s_or_b32 s4, s4, s80
	s_and_b32 s78, s5, 0xffc0
	s_and_b32 s5, s12, 0x3ff00
	s_mulk_i32 s4, 0x3000
	v_mov_b32_e32 v2, 0
	s_or_b32 s12, s5, s4
	s_mov_b32 s45, 0
	v_mov_b32_e32 v3, v2
	v_mov_b32_e32 v0, v2
	v_mov_b32_e32 v1, v2
	v_lshl_add_u64 v[4:5], v[4:5], 0, s[12:13]
	s_waitcnt vmcnt(4)
	v_mul_f32_e32 v10, 0xbfb8aa3b, v6
	s_waitcnt vmcnt(3)
	v_mul_f32_e32 v11, 0xbfb8aa3b, v7
	s_waitcnt vmcnt(2)
	v_mul_f32_e32 v12, 0xbfb8aa3b, v8
	s_waitcnt vmcnt(1)
	v_mul_f32_e32 v13, 0xbfb8aa3b, v9
	v_exp_f32_e32 v10, v10
	v_exp_f32_e32 v11, v11
	s_waitcnt vmcnt(0)
	v_mul_f32_e32 v15, 0xbfb8aa3b, v14
	v_exp_f32_e32 v12, v12
	v_exp_f32_e32 v13, v13
	v_exp_f32_e32 v15, v15
	v_add_f32_e32 v10, 1.0, v10
	v_add_f32_e32 v11, 1.0, v11
	v_add_f32_e32 v12, 1.0, v12
	v_add_f32_e32 v13, 1.0, v13
	v_add_f32_e32 v15, 1.0, v15
	v_rcp_f32_e32 v10, v10
	v_rcp_f32_e32 v11, v11
	v_rcp_f32_e32 v12, v12
	v_rcp_f32_e32 v13, v13
	v_rcp_f32_e32 v15, v15
	v_mul_f32_e32 v10, v6, v10
	v_mul_f32_e32 v11, v7, v11
	v_mul_f32_e32 v12, v8, v12
	v_mul_f32_e32 v13, v9, v13
	v_mul_f32_e32 v14, v14, v15
	v_mov_b32_e32 v9, v2
	v_readfirstlane_b32 s4, v4
	v_readfirstlane_b32 s5, v5
	s_nop 4
	s_sub_u32 s4, s4, 0x18000
	s_subb_u32 s5, s5, 0
	global_load_dword v16, v132, s[4:5] nt
	s_add_u32 s4, s4, 0x3000
	s_addc_u32 s5, s5, 0
	global_load_dword v17, v132, s[4:5] nt
	s_add_u32 s4, s4, 0x3000
	s_addc_u32 s5, s5, 0
	global_load_dword v18, v132, s[4:5] nt
	s_add_u32 s4, s4, 0x3000
	s_addc_u32 s5, s5, 0
	global_load_dword v19, v132, s[4:5] nt
	s_add_u32 s4, s4, 0x3000
	s_addc_u32 s5, s5, 0
	global_load_dword v20, v132, s[4:5] nt
	s_add_u32 s4, s4, 0x3000
	s_addc_u32 s5, s5, 0
	global_load_dword v21, v132, s[4:5] nt
	s_add_u32 s4, s4, 0x3000
	s_addc_u32 s5, s5, 0
	global_load_dword v22, v132, s[4:5] nt
	s_add_u32 s4, s4, 0x3000
	s_addc_u32 s5, s5, 0
	global_load_dword v23, v132, s[4:5] nt
	s_add_u32 s4, s4, 0x3000
	s_addc_u32 s5, s5, 0
	global_load_dword v24, v132, s[4:5] nt
	s_add_u32 s4, s4, 0x3000
	s_addc_u32 s5, s5, 0
	global_load_dword v25, v132, s[4:5] nt
	s_add_u32 s4, s4, 0x3000
	s_addc_u32 s5, s5, 0
	global_load_dword v26, v132, s[4:5] nt
	s_add_u32 s4, s4, 0x3000
	s_addc_u32 s5, s5, 0
	global_load_dword v27, v132, s[4:5] nt
	s_add_u32 s4, s4, 0x3000
	s_addc_u32 s5, s5, 0
	global_load_dword v28, v132, s[4:5] nt
	s_add_u32 s4, s4, 0x3000
	s_addc_u32 s5, s5, 0
	global_load_dword v29, v132, s[4:5] nt
	s_add_u32 s4, s4, 0x3000
	s_addc_u32 s5, s5, 0
	global_load_dword v30, v132, s[4:5] nt
	s_add_u32 s4, s4, 0x3000
	s_addc_u32 s5, s5, 0
	global_load_dword v31, v132, s[4:5] nt
	s_add_u32 s4, s4, 0x3000
	s_addc_u32 s5, s5, 0
	global_load_dword v32, v132, s[4:5] nt
	s_add_u32 s4, s4, 0x3000
	s_addc_u32 s5, s5, 0
	global_load_dword v33, v132, s[4:5] nt
	s_add_u32 s4, s4, 0x3000
	s_addc_u32 s5, s5, 0
	global_load_dword v34, v132, s[4:5] nt
	s_add_u32 s4, s4, 0x3000
	s_addc_u32 s5, s5, 0
	global_load_dword v35, v132, s[4:5] nt
	s_add_u32 s4, s4, 0x3000
	s_addc_u32 s5, s5, 0
	global_load_dword v36, v132, s[4:5] nt
	s_add_u32 s4, s4, 0x3000
	s_addc_u32 s5, s5, 0
	global_load_dword v37, v132, s[4:5] nt
	s_add_u32 s4, s4, 0x3000
	s_addc_u32 s5, s5, 0
	global_load_dword v38, v132, s[4:5] nt
	s_add_u32 s4, s4, 0x3000
	s_addc_u32 s5, s5, 0
	global_load_dword v39, v132, s[4:5] nt
	s_add_u32 s4, s4, 0x3000
	s_addc_u32 s5, s5, 0
	global_load_dword v40, v132, s[4:5] nt
	s_add_u32 s4, s4, 0x3000
	s_addc_u32 s5, s5, 0
	global_load_dword v41, v132, s[4:5] nt
	s_add_u32 s4, s4, 0x3000
	s_addc_u32 s5, s5, 0
	global_load_dword v42, v132, s[4:5] nt
	s_add_u32 s4, s4, 0x3000
	s_addc_u32 s5, s5, 0
	global_load_dword v43, v132, s[4:5] nt
	s_add_u32 s4, s4, 0x3000
	s_addc_u32 s5, s5, 0
	global_load_dword v44, v132, s[4:5] nt
	s_add_u32 s4, s4, 0x3000
	s_addc_u32 s5, s5, 0
	global_load_dword v45, v132, s[4:5] nt
	s_add_u32 s4, s4, 0x3000
	s_addc_u32 s5, s5, 0
	global_load_dword v46, v132, s[4:5] nt
	s_add_u32 s4, s4, 0x3000
	s_addc_u32 s5, s5, 0
	global_load_dword v47, v132, s[4:5] nt
	s_add_u32 s4, s4, 0x3000
	s_addc_u32 s5, s5, 0
	global_load_dword v48, v132, s[4:5] nt
	s_add_u32 s4, s4, 0x3000
	s_addc_u32 s5, s5, 0
	global_load_dword v49, v132, s[4:5] nt
	s_add_u32 s4, s4, 0x3000
	s_addc_u32 s5, s5, 0
	global_load_dword v50, v132, s[4:5] nt
	s_add_u32 s4, s4, 0x3000
	s_addc_u32 s5, s5, 0
	global_load_dword v51, v132, s[4:5] nt
	s_add_u32 s4, s4, 0x3000
	s_addc_u32 s5, s5, 0
	global_load_dword v52, v132, s[4:5] nt
	s_add_u32 s4, s4, 0x3000
	s_addc_u32 s5, s5, 0
	global_load_dword v53, v132, s[4:5] nt
	s_add_u32 s4, s4, 0x3000
	s_addc_u32 s5, s5, 0
	global_load_dword v54, v132, s[4:5] nt
	s_add_u32 s4, s4, 0x3000
	s_addc_u32 s5, s5, 0
	global_load_dword v55, v132, s[4:5] nt
	s_add_u32 s4, s4, 0x3000
	s_addc_u32 s5, s5, 0
	global_load_dword v56, v132, s[4:5] nt
	s_add_u32 s4, s4, 0x3000
	s_addc_u32 s5, s5, 0
	global_load_dword v57, v132, s[4:5] nt
	s_add_u32 s4, s4, 0x3000
	s_addc_u32 s5, s5, 0
	global_load_dword v58, v132, s[4:5] nt
	s_add_u32 s4, s4, 0x3000
	s_addc_u32 s5, s5, 0
	global_load_dword v59, v132, s[4:5] nt
	s_add_u32 s4, s4, 0x3000
	s_addc_u32 s5, s5, 0
	global_load_dword v60, v132, s[4:5] nt
	s_add_u32 s4, s4, 0x3000
	s_addc_u32 s5, s5, 0
	global_load_dword v61, v132, s[4:5] nt
	s_add_u32 s4, s4, 0x3000
	s_addc_u32 s5, s5, 0
	global_load_dword v62, v132, s[4:5] nt
	s_add_u32 s4, s4, 0x3000
	s_addc_u32 s5, s5, 0
	global_load_dword v63, v132, s[4:5] nt
	s_add_u32 s4, s4, 0x3000
	s_addc_u32 s5, s5, 0
	global_load_dword v64, v132, s[4:5] nt
	s_add_u32 s4, s4, 0x3000
	s_addc_u32 s5, s5, 0
	global_load_dword v65, v132, s[4:5] nt
	s_add_u32 s4, s4, 0x3000
	s_addc_u32 s5, s5, 0
	global_load_dword v66, v132, s[4:5] nt
	s_add_u32 s4, s4, 0x3000
	s_addc_u32 s5, s5, 0
	global_load_dword v67, v132, s[4:5] nt
	s_add_u32 s4, s4, 0x3000
	s_addc_u32 s5, s5, 0
	global_load_dword v68, v132, s[4:5] nt
	s_add_u32 s4, s4, 0x3000
	s_addc_u32 s5, s5, 0
	global_load_dword v69, v132, s[4:5] nt
	s_add_u32 s4, s4, 0x3000
	s_addc_u32 s5, s5, 0
	global_load_dword v70, v132, s[4:5] nt
	s_add_u32 s4, s4, 0x3000
	s_addc_u32 s5, s5, 0
	global_load_dword v71, v132, s[4:5] nt
	s_add_u32 s4, s4, 0x3000
	s_addc_u32 s5, s5, 0
	global_load_dword v72, v132, s[4:5] nt
	s_add_u32 s4, s4, 0x3000
	s_addc_u32 s5, s5, 0
	global_load_dword v73, v132, s[4:5] nt
	s_add_u32 s4, s4, 0x3000
	s_addc_u32 s5, s5, 0
	global_load_dword v74, v132, s[4:5] nt
	s_add_u32 s4, s4, 0x3000
	s_addc_u32 s5, s5, 0
	global_load_dword v75, v132, s[4:5] nt
	s_add_u32 s4, s4, 0x3000
	s_addc_u32 s5, s5, 0
	global_load_dword v76, v132, s[4:5] nt
	s_add_u32 s4, s4, 0x3000
	s_addc_u32 s5, s5, 0
	global_load_dword v77, v132, s[4:5] nt
	s_add_u32 s4, s4, 0x3000
	s_addc_u32 s5, s5, 0
	global_load_dword v78, v132, s[4:5] nt
	s_add_u32 s4, s4, 0x3000
	s_addc_u32 s5, s5, 0
	global_load_dword v79, v132, s[4:5] nt
	v_readlane_b32 s82, v10, 0
	v_readlane_b32 s83, v11, 0
	v_readlane_b32 s84, v12, 0
	v_readlane_b32 s85, v13, 0
	v_readlane_b32 s86, v14, 0
	v_readlane_b32 s87, v10, 1
	v_readlane_b32 s88, v11, 1
	v_readlane_b32 s89, v12, 1
	v_readlane_b32 s79, v13, 1
	v_readlane_b32 s80, v14, 1
	s_waitcnt vmcnt(62)
	v_fmac_f32_e32 v2, s82, v16
	v_fmac_f32_e32 v3, s83, v16
	v_fmac_f32_e32 v0, s84, v16
	v_fmac_f32_e32 v1, s85, v16
	v_fmac_f32_e32 v9, s86, v16
	v_fmac_f32_e32 v2, s87, v17
	v_fmac_f32_e32 v3, s88, v17
	v_fmac_f32_e32 v0, s89, v17
	v_fmac_f32_e32 v1, s79, v17
	v_fmac_f32_e32 v9, s80, v17
	v_readlane_b32 s82, v10, 2
	v_readlane_b32 s83, v11, 2
	v_readlane_b32 s84, v12, 2
	v_readlane_b32 s85, v13, 2
	v_readlane_b32 s86, v14, 2
	v_readlane_b32 s87, v10, 3
	v_readlane_b32 s88, v11, 3
	v_readlane_b32 s89, v12, 3
	v_readlane_b32 s79, v13, 3
	v_readlane_b32 s80, v14, 3
	s_waitcnt vmcnt(60)
	v_fmac_f32_e32 v2, s82, v18
	v_fmac_f32_e32 v3, s83, v18
	v_fmac_f32_e32 v0, s84, v18
	v_fmac_f32_e32 v1, s85, v18
	v_fmac_f32_e32 v9, s86, v18
	v_fmac_f32_e32 v2, s87, v19
	v_fmac_f32_e32 v3, s88, v19
	v_fmac_f32_e32 v0, s89, v19
	v_fmac_f32_e32 v1, s79, v19
	v_fmac_f32_e32 v9, s80, v19
	v_readlane_b32 s82, v10, 4
	v_readlane_b32 s83, v11, 4
	v_readlane_b32 s84, v12, 4
	v_readlane_b32 s85, v13, 4
	v_readlane_b32 s86, v14, 4
	v_readlane_b32 s87, v10, 5
	v_readlane_b32 s88, v11, 5
	v_readlane_b32 s89, v12, 5
	v_readlane_b32 s79, v13, 5
	v_readlane_b32 s80, v14, 5
	s_waitcnt vmcnt(58)
	v_fmac_f32_e32 v2, s82, v20
	v_fmac_f32_e32 v3, s83, v20
	v_fmac_f32_e32 v0, s84, v20
	v_fmac_f32_e32 v1, s85, v20
	v_fmac_f32_e32 v9, s86, v20
	v_fmac_f32_e32 v2, s87, v21
	v_fmac_f32_e32 v3, s88, v21
	v_fmac_f32_e32 v0, s89, v21
	v_fmac_f32_e32 v1, s79, v21
	v_fmac_f32_e32 v9, s80, v21
	v_readlane_b32 s82, v10, 6
	v_readlane_b32 s83, v11, 6
	v_readlane_b32 s84, v12, 6
	v_readlane_b32 s85, v13, 6
	v_readlane_b32 s86, v14, 6
	v_readlane_b32 s87, v10, 7
	v_readlane_b32 s88, v11, 7
	v_readlane_b32 s89, v12, 7
	v_readlane_b32 s79, v13, 7
	v_readlane_b32 s80, v14, 7
	s_waitcnt vmcnt(56)
	v_fmac_f32_e32 v2, s82, v22
	v_fmac_f32_e32 v3, s83, v22
	v_fmac_f32_e32 v0, s84, v22
	v_fmac_f32_e32 v1, s85, v22
	v_fmac_f32_e32 v9, s86, v22
	v_fmac_f32_e32 v2, s87, v23
	v_fmac_f32_e32 v3, s88, v23
	v_fmac_f32_e32 v0, s89, v23
	v_fmac_f32_e32 v1, s79, v23
	v_fmac_f32_e32 v9, s80, v23
	v_readlane_b32 s82, v10, 8
	v_readlane_b32 s83, v11, 8
	v_readlane_b32 s84, v12, 8
	v_readlane_b32 s85, v13, 8
	v_readlane_b32 s86, v14, 8
	v_readlane_b32 s87, v10, 9
	v_readlane_b32 s88, v11, 9
	v_readlane_b32 s89, v12, 9
	v_readlane_b32 s79, v13, 9
	v_readlane_b32 s80, v14, 9
	s_waitcnt vmcnt(54)
	v_fmac_f32_e32 v2, s82, v24
	v_fmac_f32_e32 v3, s83, v24
	v_fmac_f32_e32 v0, s84, v24
	v_fmac_f32_e32 v1, s85, v24
	v_fmac_f32_e32 v9, s86, v24
	v_fmac_f32_e32 v2, s87, v25
	v_fmac_f32_e32 v3, s88, v25
	v_fmac_f32_e32 v0, s89, v25
	v_fmac_f32_e32 v1, s79, v25
	v_fmac_f32_e32 v9, s80, v25
	v_readlane_b32 s82, v10, 10
	v_readlane_b32 s83, v11, 10
	v_readlane_b32 s84, v12, 10
	v_readlane_b32 s85, v13, 10
	v_readlane_b32 s86, v14, 10
	v_readlane_b32 s87, v10, 11
	v_readlane_b32 s88, v11, 11
	v_readlane_b32 s89, v12, 11
	v_readlane_b32 s79, v13, 11
	v_readlane_b32 s80, v14, 11
	s_waitcnt vmcnt(52)
	v_fmac_f32_e32 v2, s82, v26
	v_fmac_f32_e32 v3, s83, v26
	v_fmac_f32_e32 v0, s84, v26
	v_fmac_f32_e32 v1, s85, v26
	v_fmac_f32_e32 v9, s86, v26
	v_fmac_f32_e32 v2, s87, v27
	v_fmac_f32_e32 v3, s88, v27
	v_fmac_f32_e32 v0, s89, v27
	v_fmac_f32_e32 v1, s79, v27
	v_fmac_f32_e32 v9, s80, v27
	v_readlane_b32 s82, v10, 12
	v_readlane_b32 s83, v11, 12
	v_readlane_b32 s84, v12, 12
	v_readlane_b32 s85, v13, 12
	v_readlane_b32 s86, v14, 12
	v_readlane_b32 s87, v10, 13
	v_readlane_b32 s88, v11, 13
	v_readlane_b32 s89, v12, 13
	v_readlane_b32 s79, v13, 13
	v_readlane_b32 s80, v14, 13
	s_waitcnt vmcnt(50)
	v_fmac_f32_e32 v2, s82, v28
	v_fmac_f32_e32 v3, s83, v28
	v_fmac_f32_e32 v0, s84, v28
	v_fmac_f32_e32 v1, s85, v28
	v_fmac_f32_e32 v9, s86, v28
	v_fmac_f32_e32 v2, s87, v29
	v_fmac_f32_e32 v3, s88, v29
	v_fmac_f32_e32 v0, s89, v29
	v_fmac_f32_e32 v1, s79, v29
	v_fmac_f32_e32 v9, s80, v29
	v_readlane_b32 s82, v10, 14
	v_readlane_b32 s83, v11, 14
	v_readlane_b32 s84, v12, 14
	v_readlane_b32 s85, v13, 14
	v_readlane_b32 s86, v14, 14
	v_readlane_b32 s87, v10, 15
	v_readlane_b32 s88, v11, 15
	v_readlane_b32 s89, v12, 15
	v_readlane_b32 s79, v13, 15
	v_readlane_b32 s80, v14, 15
	s_waitcnt vmcnt(48)
	v_fmac_f32_e32 v2, s82, v30
	v_fmac_f32_e32 v3, s83, v30
	v_fmac_f32_e32 v0, s84, v30
	v_fmac_f32_e32 v1, s85, v30
	v_fmac_f32_e32 v9, s86, v30
	v_fmac_f32_e32 v2, s87, v31
	v_fmac_f32_e32 v3, s88, v31
	v_fmac_f32_e32 v0, s89, v31
	v_fmac_f32_e32 v1, s79, v31
	v_fmac_f32_e32 v9, s80, v31
	v_readlane_b32 s82, v10, 16
	v_readlane_b32 s83, v11, 16
	v_readlane_b32 s84, v12, 16
	v_readlane_b32 s85, v13, 16
	v_readlane_b32 s86, v14, 16
	v_readlane_b32 s87, v10, 17
	v_readlane_b32 s88, v11, 17
	v_readlane_b32 s89, v12, 17
	v_readlane_b32 s79, v13, 17
	v_readlane_b32 s80, v14, 17
	s_waitcnt vmcnt(46)
	v_fmac_f32_e32 v2, s82, v32
	v_fmac_f32_e32 v3, s83, v32
	v_fmac_f32_e32 v0, s84, v32
	v_fmac_f32_e32 v1, s85, v32
	v_fmac_f32_e32 v9, s86, v32
	v_fmac_f32_e32 v2, s87, v33
	v_fmac_f32_e32 v3, s88, v33
	v_fmac_f32_e32 v0, s89, v33
	v_fmac_f32_e32 v1, s79, v33
	v_fmac_f32_e32 v9, s80, v33
	v_readlane_b32 s82, v10, 18
	v_readlane_b32 s83, v11, 18
	v_readlane_b32 s84, v12, 18
	v_readlane_b32 s85, v13, 18
	v_readlane_b32 s86, v14, 18
	v_readlane_b32 s87, v10, 19
	v_readlane_b32 s88, v11, 19
	v_readlane_b32 s89, v12, 19
	v_readlane_b32 s79, v13, 19
	v_readlane_b32 s80, v14, 19
	s_waitcnt vmcnt(44)
	v_fmac_f32_e32 v2, s82, v34
	v_fmac_f32_e32 v3, s83, v34
	v_fmac_f32_e32 v0, s84, v34
	v_fmac_f32_e32 v1, s85, v34
	v_fmac_f32_e32 v9, s86, v34
	v_fmac_f32_e32 v2, s87, v35
	v_fmac_f32_e32 v3, s88, v35
	v_fmac_f32_e32 v0, s89, v35
	v_fmac_f32_e32 v1, s79, v35
	v_fmac_f32_e32 v9, s80, v35
	v_readlane_b32 s82, v10, 20
	v_readlane_b32 s83, v11, 20
	v_readlane_b32 s84, v12, 20
	v_readlane_b32 s85, v13, 20
	v_readlane_b32 s86, v14, 20
	v_readlane_b32 s87, v10, 21
	v_readlane_b32 s88, v11, 21
	v_readlane_b32 s89, v12, 21
	v_readlane_b32 s79, v13, 21
	v_readlane_b32 s80, v14, 21
	s_waitcnt vmcnt(42)
	v_fmac_f32_e32 v2, s82, v36
	v_fmac_f32_e32 v3, s83, v36
	v_fmac_f32_e32 v0, s84, v36
	v_fmac_f32_e32 v1, s85, v36
	v_fmac_f32_e32 v9, s86, v36
	v_fmac_f32_e32 v2, s87, v37
	v_fmac_f32_e32 v3, s88, v37
	v_fmac_f32_e32 v0, s89, v37
	v_fmac_f32_e32 v1, s79, v37
	v_fmac_f32_e32 v9, s80, v37
	v_readlane_b32 s82, v10, 22
	v_readlane_b32 s83, v11, 22
	v_readlane_b32 s84, v12, 22
	v_readlane_b32 s85, v13, 22
	v_readlane_b32 s86, v14, 22
	v_readlane_b32 s87, v10, 23
	v_readlane_b32 s88, v11, 23
	v_readlane_b32 s89, v12, 23
	v_readlane_b32 s79, v13, 23
	v_readlane_b32 s80, v14, 23
	s_waitcnt vmcnt(40)
	v_fmac_f32_e32 v2, s82, v38
	v_fmac_f32_e32 v3, s83, v38
	v_fmac_f32_e32 v0, s84, v38
	v_fmac_f32_e32 v1, s85, v38
	v_fmac_f32_e32 v9, s86, v38
	v_fmac_f32_e32 v2, s87, v39
	v_fmac_f32_e32 v3, s88, v39
	v_fmac_f32_e32 v0, s89, v39
	v_fmac_f32_e32 v1, s79, v39
	v_fmac_f32_e32 v9, s80, v39
	v_readlane_b32 s82, v10, 24
	v_readlane_b32 s83, v11, 24
	v_readlane_b32 s84, v12, 24
	v_readlane_b32 s85, v13, 24
	v_readlane_b32 s86, v14, 24
	v_readlane_b32 s87, v10, 25
	v_readlane_b32 s88, v11, 25
	v_readlane_b32 s89, v12, 25
	v_readlane_b32 s79, v13, 25
	v_readlane_b32 s80, v14, 25
	s_waitcnt vmcnt(38)
	v_fmac_f32_e32 v2, s82, v40
	v_fmac_f32_e32 v3, s83, v40
	v_fmac_f32_e32 v0, s84, v40
	v_fmac_f32_e32 v1, s85, v40
	v_fmac_f32_e32 v9, s86, v40
	v_fmac_f32_e32 v2, s87, v41
	v_fmac_f32_e32 v3, s88, v41
	v_fmac_f32_e32 v0, s89, v41
	v_fmac_f32_e32 v1, s79, v41
	v_fmac_f32_e32 v9, s80, v41
	v_readlane_b32 s82, v10, 26
	v_readlane_b32 s83, v11, 26
	v_readlane_b32 s84, v12, 26
	v_readlane_b32 s85, v13, 26
	v_readlane_b32 s86, v14, 26
	v_readlane_b32 s87, v10, 27
	v_readlane_b32 s88, v11, 27
	v_readlane_b32 s89, v12, 27
	v_readlane_b32 s79, v13, 27
	v_readlane_b32 s80, v14, 27
	s_waitcnt vmcnt(36)
	v_fmac_f32_e32 v2, s82, v42
	v_fmac_f32_e32 v3, s83, v42
	v_fmac_f32_e32 v0, s84, v42
	v_fmac_f32_e32 v1, s85, v42
	v_fmac_f32_e32 v9, s86, v42
	v_fmac_f32_e32 v2, s87, v43
	v_fmac_f32_e32 v3, s88, v43
	v_fmac_f32_e32 v0, s89, v43
	v_fmac_f32_e32 v1, s79, v43
	v_fmac_f32_e32 v9, s80, v43
	v_readlane_b32 s82, v10, 28
	v_readlane_b32 s83, v11, 28
	v_readlane_b32 s84, v12, 28
	v_readlane_b32 s85, v13, 28
	v_readlane_b32 s86, v14, 28
	v_readlane_b32 s87, v10, 29
	v_readlane_b32 s88, v11, 29
	v_readlane_b32 s89, v12, 29
	v_readlane_b32 s79, v13, 29
	v_readlane_b32 s80, v14, 29
	s_waitcnt vmcnt(34)
	v_fmac_f32_e32 v2, s82, v44
	v_fmac_f32_e32 v3, s83, v44
	v_fmac_f32_e32 v0, s84, v44
	v_fmac_f32_e32 v1, s85, v44
	v_fmac_f32_e32 v9, s86, v44
	v_fmac_f32_e32 v2, s87, v45
	v_fmac_f32_e32 v3, s88, v45
	v_fmac_f32_e32 v0, s89, v45
	v_fmac_f32_e32 v1, s79, v45
	v_fmac_f32_e32 v9, s80, v45
	v_readlane_b32 s82, v10, 30
	v_readlane_b32 s83, v11, 30
	v_readlane_b32 s84, v12, 30
	v_readlane_b32 s85, v13, 30
	v_readlane_b32 s86, v14, 30
	v_readlane_b32 s87, v10, 31
	v_readlane_b32 s88, v11, 31
	v_readlane_b32 s89, v12, 31
	v_readlane_b32 s79, v13, 31
	v_readlane_b32 s80, v14, 31
	s_waitcnt vmcnt(32)
	v_fmac_f32_e32 v2, s82, v46
	v_fmac_f32_e32 v3, s83, v46
	v_fmac_f32_e32 v0, s84, v46
	v_fmac_f32_e32 v1, s85, v46
	v_fmac_f32_e32 v9, s86, v46
	v_fmac_f32_e32 v2, s87, v47
	v_fmac_f32_e32 v3, s88, v47
	v_fmac_f32_e32 v0, s89, v47
	v_fmac_f32_e32 v1, s79, v47
	v_fmac_f32_e32 v9, s80, v47
	v_readlane_b32 s82, v10, 32
	v_readlane_b32 s83, v11, 32
	v_readlane_b32 s84, v12, 32
	v_readlane_b32 s85, v13, 32
	v_readlane_b32 s86, v14, 32
	v_readlane_b32 s87, v10, 33
	v_readlane_b32 s88, v11, 33
	v_readlane_b32 s89, v12, 33
	v_readlane_b32 s79, v13, 33
	v_readlane_b32 s80, v14, 33
	s_waitcnt vmcnt(30)
	v_fmac_f32_e32 v2, s82, v48
	v_fmac_f32_e32 v3, s83, v48
	v_fmac_f32_e32 v0, s84, v48
	v_fmac_f32_e32 v1, s85, v48
	v_fmac_f32_e32 v9, s86, v48
	v_fmac_f32_e32 v2, s87, v49
	v_fmac_f32_e32 v3, s88, v49
	v_fmac_f32_e32 v0, s89, v49
	v_fmac_f32_e32 v1, s79, v49
	v_fmac_f32_e32 v9, s80, v49
	v_readlane_b32 s82, v10, 34
	v_readlane_b32 s83, v11, 34
	v_readlane_b32 s84, v12, 34
	v_readlane_b32 s85, v13, 34
	v_readlane_b32 s86, v14, 34
	v_readlane_b32 s87, v10, 35
	v_readlane_b32 s88, v11, 35
	v_readlane_b32 s89, v12, 35
	v_readlane_b32 s79, v13, 35
	v_readlane_b32 s80, v14, 35
	s_waitcnt vmcnt(28)
	v_fmac_f32_e32 v2, s82, v50
	v_fmac_f32_e32 v3, s83, v50
	v_fmac_f32_e32 v0, s84, v50
	v_fmac_f32_e32 v1, s85, v50
	v_fmac_f32_e32 v9, s86, v50
	v_fmac_f32_e32 v2, s87, v51
	v_fmac_f32_e32 v3, s88, v51
	v_fmac_f32_e32 v0, s89, v51
	v_fmac_f32_e32 v1, s79, v51
	v_fmac_f32_e32 v9, s80, v51
	v_readlane_b32 s82, v10, 36
	v_readlane_b32 s83, v11, 36
	v_readlane_b32 s84, v12, 36
	v_readlane_b32 s85, v13, 36
	v_readlane_b32 s86, v14, 36
	v_readlane_b32 s87, v10, 37
	v_readlane_b32 s88, v11, 37
	v_readlane_b32 s89, v12, 37
	v_readlane_b32 s79, v13, 37
	v_readlane_b32 s80, v14, 37
	s_waitcnt vmcnt(26)
	v_fmac_f32_e32 v2, s82, v52
	v_fmac_f32_e32 v3, s83, v52
	v_fmac_f32_e32 v0, s84, v52
	v_fmac_f32_e32 v1, s85, v52
	v_fmac_f32_e32 v9, s86, v52
	v_fmac_f32_e32 v2, s87, v53
	v_fmac_f32_e32 v3, s88, v53
	v_fmac_f32_e32 v0, s89, v53
	v_fmac_f32_e32 v1, s79, v53
	v_fmac_f32_e32 v9, s80, v53
	v_readlane_b32 s82, v10, 38
	v_readlane_b32 s83, v11, 38
	v_readlane_b32 s84, v12, 38
	v_readlane_b32 s85, v13, 38
	v_readlane_b32 s86, v14, 38
	v_readlane_b32 s87, v10, 39
	v_readlane_b32 s88, v11, 39
	v_readlane_b32 s89, v12, 39
	v_readlane_b32 s79, v13, 39
	v_readlane_b32 s80, v14, 39
	s_waitcnt vmcnt(24)
	v_fmac_f32_e32 v2, s82, v54
	v_fmac_f32_e32 v3, s83, v54
	v_fmac_f32_e32 v0, s84, v54
	v_fmac_f32_e32 v1, s85, v54
	v_fmac_f32_e32 v9, s86, v54
	v_fmac_f32_e32 v2, s87, v55
	v_fmac_f32_e32 v3, s88, v55
	v_fmac_f32_e32 v0, s89, v55
	v_fmac_f32_e32 v1, s79, v55
	v_fmac_f32_e32 v9, s80, v55
	v_readlane_b32 s82, v10, 40
	v_readlane_b32 s83, v11, 40
	v_readlane_b32 s84, v12, 40
	v_readlane_b32 s85, v13, 40
	v_readlane_b32 s86, v14, 40
	v_readlane_b32 s87, v10, 41
	v_readlane_b32 s88, v11, 41
	v_readlane_b32 s89, v12, 41
	v_readlane_b32 s79, v13, 41
	v_readlane_b32 s80, v14, 41
	s_waitcnt vmcnt(22)
	v_fmac_f32_e32 v2, s82, v56
	v_fmac_f32_e32 v3, s83, v56
	v_fmac_f32_e32 v0, s84, v56
	v_fmac_f32_e32 v1, s85, v56
	v_fmac_f32_e32 v9, s86, v56
	v_fmac_f32_e32 v2, s87, v57
	v_fmac_f32_e32 v3, s88, v57
	v_fmac_f32_e32 v0, s89, v57
	v_fmac_f32_e32 v1, s79, v57
	v_fmac_f32_e32 v9, s80, v57
	v_readlane_b32 s82, v10, 42
	v_readlane_b32 s83, v11, 42
	v_readlane_b32 s84, v12, 42
	v_readlane_b32 s85, v13, 42
	v_readlane_b32 s86, v14, 42
	v_readlane_b32 s87, v10, 43
	v_readlane_b32 s88, v11, 43
	v_readlane_b32 s89, v12, 43
	v_readlane_b32 s79, v13, 43
	v_readlane_b32 s80, v14, 43
	s_waitcnt vmcnt(20)
	v_fmac_f32_e32 v2, s82, v58
	v_fmac_f32_e32 v3, s83, v58
	v_fmac_f32_e32 v0, s84, v58
	v_fmac_f32_e32 v1, s85, v58
	v_fmac_f32_e32 v9, s86, v58
	v_fmac_f32_e32 v2, s87, v59
	v_fmac_f32_e32 v3, s88, v59
	v_fmac_f32_e32 v0, s89, v59
	v_fmac_f32_e32 v1, s79, v59
	v_fmac_f32_e32 v9, s80, v59
	v_readlane_b32 s82, v10, 44
	v_readlane_b32 s83, v11, 44
	v_readlane_b32 s84, v12, 44
	v_readlane_b32 s85, v13, 44
	v_readlane_b32 s86, v14, 44
	v_readlane_b32 s87, v10, 45
	v_readlane_b32 s88, v11, 45
	v_readlane_b32 s89, v12, 45
	v_readlane_b32 s79, v13, 45
	v_readlane_b32 s80, v14, 45
	s_waitcnt vmcnt(18)
	v_fmac_f32_e32 v2, s82, v60
	v_fmac_f32_e32 v3, s83, v60
	v_fmac_f32_e32 v0, s84, v60
	v_fmac_f32_e32 v1, s85, v60
	v_fmac_f32_e32 v9, s86, v60
	v_fmac_f32_e32 v2, s87, v61
	v_fmac_f32_e32 v3, s88, v61
	v_fmac_f32_e32 v0, s89, v61
	v_fmac_f32_e32 v1, s79, v61
	v_fmac_f32_e32 v9, s80, v61
	v_readlane_b32 s82, v10, 46
	v_readlane_b32 s83, v11, 46
	v_readlane_b32 s84, v12, 46
	v_readlane_b32 s85, v13, 46
	v_readlane_b32 s86, v14, 46
	v_readlane_b32 s87, v10, 47
	v_readlane_b32 s88, v11, 47
	v_readlane_b32 s89, v12, 47
	v_readlane_b32 s79, v13, 47
	v_readlane_b32 s80, v14, 47
	s_waitcnt vmcnt(16)
	v_fmac_f32_e32 v2, s82, v62
	v_fmac_f32_e32 v3, s83, v62
	v_fmac_f32_e32 v0, s84, v62
	v_fmac_f32_e32 v1, s85, v62
	v_fmac_f32_e32 v9, s86, v62
	v_fmac_f32_e32 v2, s87, v63
	v_fmac_f32_e32 v3, s88, v63
	v_fmac_f32_e32 v0, s89, v63
	v_fmac_f32_e32 v1, s79, v63
	v_fmac_f32_e32 v9, s80, v63
	v_readlane_b32 s82, v10, 48
	v_readlane_b32 s83, v11, 48
	v_readlane_b32 s84, v12, 48
	v_readlane_b32 s85, v13, 48
	v_readlane_b32 s86, v14, 48
	v_readlane_b32 s87, v10, 49
	v_readlane_b32 s88, v11, 49
	v_readlane_b32 s89, v12, 49
	v_readlane_b32 s79, v13, 49
	v_readlane_b32 s80, v14, 49
	s_waitcnt vmcnt(14)
	v_fmac_f32_e32 v2, s82, v64
	v_fmac_f32_e32 v3, s83, v64
	v_fmac_f32_e32 v0, s84, v64
	v_fmac_f32_e32 v1, s85, v64
	v_fmac_f32_e32 v9, s86, v64
	v_fmac_f32_e32 v2, s87, v65
	v_fmac_f32_e32 v3, s88, v65
	v_fmac_f32_e32 v0, s89, v65
	v_fmac_f32_e32 v1, s79, v65
	v_fmac_f32_e32 v9, s80, v65
	v_readlane_b32 s82, v10, 50
	v_readlane_b32 s83, v11, 50
	v_readlane_b32 s84, v12, 50
	v_readlane_b32 s85, v13, 50
	v_readlane_b32 s86, v14, 50
	v_readlane_b32 s87, v10, 51
	v_readlane_b32 s88, v11, 51
	v_readlane_b32 s89, v12, 51
	v_readlane_b32 s79, v13, 51
	v_readlane_b32 s80, v14, 51
	s_waitcnt vmcnt(12)
	v_fmac_f32_e32 v2, s82, v66
	v_fmac_f32_e32 v3, s83, v66
	v_fmac_f32_e32 v0, s84, v66
	v_fmac_f32_e32 v1, s85, v66
	v_fmac_f32_e32 v9, s86, v66
	v_fmac_f32_e32 v2, s87, v67
	v_fmac_f32_e32 v3, s88, v67
	v_fmac_f32_e32 v0, s89, v67
	v_fmac_f32_e32 v1, s79, v67
	v_fmac_f32_e32 v9, s80, v67
	v_readlane_b32 s82, v10, 52
	v_readlane_b32 s83, v11, 52
	v_readlane_b32 s84, v12, 52
	v_readlane_b32 s85, v13, 52
	v_readlane_b32 s86, v14, 52
	v_readlane_b32 s87, v10, 53
	v_readlane_b32 s88, v11, 53
	v_readlane_b32 s89, v12, 53
	v_readlane_b32 s79, v13, 53
	v_readlane_b32 s80, v14, 53
	s_waitcnt vmcnt(10)
	v_fmac_f32_e32 v2, s82, v68
	v_fmac_f32_e32 v3, s83, v68
	v_fmac_f32_e32 v0, s84, v68
	v_fmac_f32_e32 v1, s85, v68
	v_fmac_f32_e32 v9, s86, v68
	v_fmac_f32_e32 v2, s87, v69
	v_fmac_f32_e32 v3, s88, v69
	v_fmac_f32_e32 v0, s89, v69
	v_fmac_f32_e32 v1, s79, v69
	v_fmac_f32_e32 v9, s80, v69
	v_readlane_b32 s82, v10, 54
	v_readlane_b32 s83, v11, 54
	v_readlane_b32 s84, v12, 54
	v_readlane_b32 s85, v13, 54
	v_readlane_b32 s86, v14, 54
	v_readlane_b32 s87, v10, 55
	v_readlane_b32 s88, v11, 55
	v_readlane_b32 s89, v12, 55
	v_readlane_b32 s79, v13, 55
	v_readlane_b32 s80, v14, 55
	s_waitcnt vmcnt(8)
	v_fmac_f32_e32 v2, s82, v70
	v_fmac_f32_e32 v3, s83, v70
	v_fmac_f32_e32 v0, s84, v70
	v_fmac_f32_e32 v1, s85, v70
	v_fmac_f32_e32 v9, s86, v70
	v_fmac_f32_e32 v2, s87, v71
	v_fmac_f32_e32 v3, s88, v71
	v_fmac_f32_e32 v0, s89, v71
	v_fmac_f32_e32 v1, s79, v71
	v_fmac_f32_e32 v9, s80, v71
	v_readlane_b32 s82, v10, 56
	v_readlane_b32 s83, v11, 56
	v_readlane_b32 s84, v12, 56
	v_readlane_b32 s85, v13, 56
	v_readlane_b32 s86, v14, 56
	v_readlane_b32 s87, v10, 57
	v_readlane_b32 s88, v11, 57
	v_readlane_b32 s89, v12, 57
	v_readlane_b32 s79, v13, 57
	v_readlane_b32 s80, v14, 57
	s_waitcnt vmcnt(6)
	v_fmac_f32_e32 v2, s82, v72
	v_fmac_f32_e32 v3, s83, v72
	v_fmac_f32_e32 v0, s84, v72
	v_fmac_f32_e32 v1, s85, v72
	v_fmac_f32_e32 v9, s86, v72
	v_fmac_f32_e32 v2, s87, v73
	v_fmac_f32_e32 v3, s88, v73
	v_fmac_f32_e32 v0, s89, v73
	v_fmac_f32_e32 v1, s79, v73
	v_fmac_f32_e32 v9, s80, v73
	v_readlane_b32 s82, v10, 58
	v_readlane_b32 s83, v11, 58
	v_readlane_b32 s84, v12, 58
	v_readlane_b32 s85, v13, 58
	v_readlane_b32 s86, v14, 58
	v_readlane_b32 s87, v10, 59
	v_readlane_b32 s88, v11, 59
	v_readlane_b32 s89, v12, 59
	v_readlane_b32 s79, v13, 59
	v_readlane_b32 s80, v14, 59
	s_waitcnt vmcnt(4)
	v_fmac_f32_e32 v2, s82, v74
	v_fmac_f32_e32 v3, s83, v74
	v_fmac_f32_e32 v0, s84, v74
	v_fmac_f32_e32 v1, s85, v74
	v_fmac_f32_e32 v9, s86, v74
	v_fmac_f32_e32 v2, s87, v75
	v_fmac_f32_e32 v3, s88, v75
	v_fmac_f32_e32 v0, s89, v75
	v_fmac_f32_e32 v1, s79, v75
	v_fmac_f32_e32 v9, s80, v75
	v_readlane_b32 s82, v10, 60
	v_readlane_b32 s83, v11, 60
	v_readlane_b32 s84, v12, 60
	v_readlane_b32 s85, v13, 60
	v_readlane_b32 s86, v14, 60
	v_readlane_b32 s87, v10, 61
	v_readlane_b32 s88, v11, 61
	v_readlane_b32 s89, v12, 61
	v_readlane_b32 s79, v13, 61
	v_readlane_b32 s80, v14, 61
	s_waitcnt vmcnt(2)
	v_fmac_f32_e32 v2, s82, v76
	v_fmac_f32_e32 v3, s83, v76
	v_fmac_f32_e32 v0, s84, v76
	v_fmac_f32_e32 v1, s85, v76
	v_fmac_f32_e32 v9, s86, v76
	v_fmac_f32_e32 v2, s87, v77
	v_fmac_f32_e32 v3, s88, v77
	v_fmac_f32_e32 v0, s89, v77
	v_fmac_f32_e32 v1, s79, v77
	v_fmac_f32_e32 v9, s80, v77
	v_readlane_b32 s82, v10, 62
	v_readlane_b32 s83, v11, 62
	v_readlane_b32 s84, v12, 62
	v_readlane_b32 s85, v13, 62
	v_readlane_b32 s86, v14, 62
	v_readlane_b32 s87, v10, 63
	v_readlane_b32 s88, v11, 63
	v_readlane_b32 s89, v12, 63
	v_readlane_b32 s79, v13, 63
	v_readlane_b32 s80, v14, 63
	s_waitcnt vmcnt(0)
	v_fmac_f32_e32 v2, s82, v78
	v_fmac_f32_e32 v3, s83, v78
	v_fmac_f32_e32 v0, s84, v78
	v_fmac_f32_e32 v1, s85, v78
	v_fmac_f32_e32 v9, s86, v78
	v_fmac_f32_e32 v2, s87, v79
	v_fmac_f32_e32 v3, s88, v79
	v_fmac_f32_e32 v0, s89, v79
	v_fmac_f32_e32 v1, s79, v79
	v_fmac_f32_e32 v9, s80, v79
	s_lshl_b32 s12, s78, 2
	s_add_u32 s4, s42, s12
	s_addc_u32 s5, s43, 0
	v_lshlrev_b32_e32 v128, 2, v130
	v_cndmask_b32_e64 v6, 0, 1, s[6:7]
	v_lshl_add_u64 v[4:5], s[4:5], 0, v[128:129]
	s_lshl_b32 s4, s44, 1
	v_or_b32_e32 v6, s4, v6
	s_and_b64 s[4:5], s[6:7], exec
	s_cselect_b32 s45, 5, 0
	s_cmp_eq_u32 s44, 0
	v_readlane_b32 s80, v253, 4
	s_cselect_b64 s[4:5], -1, 0
	s_and_b64 s[6:7], s[6:7], exec
	v_readlane_b32 s81, v253, 5
	v_mul_lo_u32 v7, v6, 5
	s_cselect_b32 s44, 0xc00, 0
	s_mov_b64 s[6:7], -1
	s_and_b64 vcc, exec, s[80:81]
	s_cbranch_vccz .LBB0_89
	v_mad_u64_u32 v[10:11], s[6:7], v7, s56, v[4:5]
	global_store_dword v[10:11], v2, off
	s_mov_b64 s[6:7], 0

.LBB0_135:
	s_or_b64 exec, exec, s[12:13]
	v_cvt_f32_u32_e32 v4, v2
	s_waitcnt vmcnt(0)
	v_readfirstlane_b32 s8, v3
	v_sub_u32_e32 v3, 0, v2
	v_rcp_iflag_f32_e32 v4, v4
	v_add_u32_e32 v5, s8, v1
	v_mul_f32_e32 v4, 0x4f7ffffe, v4
	v_cvt_u32_f32_e32 v4, v4
	v_mul_lo_u32 v1, v3, v4
	v_mul_hi_u32 v1, v4, v1
	v_add_u32_e32 v1, v4, v1
	v_mul_hi_u32 v1, v5, v1
	v_mul_lo_u32 v3, v1, v2
	v_sub_u32_e32 v3, v5, v3
	v_add_u32_e32 v4, 1, v1
	v_cmp_ge_u32_e32 vcc, v3, v2
	s_nop 1
	v_cndmask_b32_e32 v1, v1, v4, vcc
	v_sub_u32_e32 v4, v3, v2
	v_cndmask_b32_e32 v3, v3, v4, vcc
	v_add_u32_e32 v4, 1, v1
	v_cmp_ge_u32_e32 vcc, v3, v2
	v_add_u32_e32 v3, 1, v5
	s_nop 0
	v_cndmask_b32_e32 v1, v1, v4, vcc
	v_mul_lo_u32 v4, v2, v1
	v_add_u32_e32 v2, v4, v2
	v_cmp_ne_u32_e32 vcc, v3, v2
	s_and_saveexec_b64 s[8:9], vcc
	s_xor_b64 s[8:9], exec, s[8:9]
	s_cbranch_execz .LBB0_149
	s_waitcnt lgkmcnt(0)
	s_add_u32 s16, s92, 0xf201500
	s_addc_u32 s17, s93, 0
	v_mov_b32_e32 v0, 0
	global_load_dword v0, v0, s[16:17] sc1
	s_waitcnt vmcnt(0)
	v_cmp_eq_u32_e32 vcc, v0, v1
	s_and_saveexec_b64 s[12:13], vcc
	s_cbranch_execz .LBB0_148
	s_add_u32 s14, s92, 0xf1fe200
	s_addc_u32 s15, s93, 0
	s_mov_b32 s28, 1
	s_mov_b64 s[18:19], 0
	v_mov_b32_e32 v0, 0
	s_branch .LBB0_139

.LBB0_174:
	s_or_b64 exec, exec, s[4:5]
	v_readfirstlane_b32 s12, v195
	s_nop 3
	s_cmp_lt_u32 s12, 0x100
	s_cbranch_scc1 .Lp1_fold
	s_mov_b32 s12, 3
	s_nop 0
	v_writelane_b32 v255, s12, 62
	s_branch .LBB0_179

.Lp1_fold_entry:
	s_load_dwordx2 s[14:15], s[8:9], 0x48
	v_readfirstlane_b32 s12, v195
	v_and_b32_e32 v123, 31, v195
	v_bfe_u32 v124, v195, 5, 1
	s_lshr_b32 s12, s12, 6
	s_lshl_b32 s4, s2, 2
	s_or_b32 s4, s4, s12
	s_and_b32 s16, s4, 7
	s_bfe_u32 s17, s4, 0x50003
	s_bfe_u32 s18, s4, 0x10008
	s_lshr_b32 s19, s4, 9
	v_mul_u32_u24_e32 v126, 0x6000, v123
	v_lshl_add_u32 v126, v124, 2, v126
	v_mov_b32_e32 v127, 0
	s_mul_i32 s5, s19, 0x1800000
	s_mul_i32 s12, s17, 0xc0000
	s_add_u32 s5, s5, s12
	s_add_u32 s5, s5, 0x2000
	s_waitcnt lgkmcnt(0)
	s_add_u32 s14, s14, s5
	s_addc_u32 s15, s15, 0
	v_lshl_add_u64 v[120:121], s[14:15], 0, v[126:127]
	v_lshlrev_b32_e32 v122, 2, v123
	v_lshl_add_u32 v122, v124, 10, v122
	s_lshl_b32 s5, s19, 1
	s_or_b32 s5, s5, s18
	s_lshl_b32 s5, s5, 18
	s_lshl_b32 s12, s16, 7
	s_add_u32 s5, s5, s12
	s_add_u32 s5, s5, 0x1ff000
	s_add_u32 s22, s6, s5
	s_addc_u32 s23, s7, 0
	s_add_u32 s24, s22, 0x2000
	s_addc_u32 s25, s23, 0
	v_mov_b32_e32 v0, 0
	v_mov_b32_e32 v1, 0
	v_mov_b32_e32 v2, 0
	v_mov_b32_e32 v3, 0
	v_mov_b32_e32 v4, 0
	v_mov_b32_e32 v5, 0
	v_mov_b32_e32 v6, 0
	v_mov_b32_e32 v7, 0
	v_mov_b32_e32 v8, 0
	v_mov_b32_e32 v9, 0
	v_mov_b32_e32 v10, 0
	v_mov_b32_e32 v11, 0
	v_mov_b32_e32 v12, 0
	v_mov_b32_e32 v13, 0
	v_mov_b32_e32 v14, 0
	v_mov_b32_e32 v15, 0
	global_load_dwordx4 v[16:19], v[120:121], off offset:0
	global_load_dwordx4 v[20:23], v[120:121], off offset:16
	global_load_dwordx4 v[24:27], v[120:121], off offset:32
	global_load_dwordx4 v[28:31], v[120:121], off offset:48
	global_load_dword v32, v122, s[22:23] offset:-4096
	global_load_dword v33, v122, s[22:23] offset:-2048
	global_load_dword v34, v122, s[22:23]
	global_load_dword v35, v122, s[22:23] offset:2048
	global_load_dword v36, v122, s[24:25] offset:-4096
	global_load_dword v37, v122, s[24:25] offset:-2048
	global_load_dword v38, v122, s[24:25]
	global_load_dword v39, v122, s[24:25] offset:2048
	s_add_u32 s22, s22, 0x4000
	s_addc_u32 s23, s23, 0
	s_add_u32 s24, s24, 0x4000
	s_addc_u32 s25, s25, 0
	global_load_dwordx4 v[40:43], v[120:121], off offset:64
	global_load_dwordx4 v[44:47], v[120:121], off offset:80
	global_load_dwordx4 v[48:51], v[120:121], off offset:96
	global_load_dwordx4 v[52:55], v[120:121], off offset:112
	global_load_dword v56, v122, s[22:23] offset:-4096
	global_load_dword v57, v122, s[22:23] offset:-2048
	global_load_dword v58, v122, s[22:23]
	global_load_dword v59, v122, s[22:23] offset:2048
	global_load_dword v60, v122, s[24:25] offset:-4096
	global_load_dword v61, v122, s[24:25] offset:-2048
	global_load_dword v62, v122, s[24:25]
	global_load_dword v63, v122, s[24:25] offset:2048
	s_add_u32 s22, s22, 0x4000
	s_addc_u32 s23, s23, 0
	s_add_u32 s24, s24, 0x4000
	s_addc_u32 s25, s25, 0
	global_load_dwordx4 v[64:67], v[120:121], off offset:128
	global_load_dwordx4 v[68:71], v[120:121], off offset:144
	global_load_dwordx4 v[72:75], v[120:121], off offset:160
	global_load_dwordx4 v[76:79], v[120:121], off offset:176
	global_load_dword v80, v122, s[22:23] offset:-4096
	global_load_dword v81, v122, s[22:23] offset:-2048
	global_load_dword v82, v122, s[22:23]
	global_load_dword v83, v122, s[22:23] offset:2048
	global_load_dword v84, v122, s[24:25] offset:-4096
	global_load_dword v85, v122, s[24:25] offset:-2048
	global_load_dword v86, v122, s[24:25]
	global_load_dword v87, v122, s[24:25] offset:2048
	s_add_u32 s22, s22, 0x4000
	s_addc_u32 s23, s23, 0
	s_add_u32 s24, s24, 0x4000
	s_addc_u32 s25, s25, 0
	v_bfe_u32 v128, v123, 2, 1
	v_bfe_u32 v129, v123, 3, 2
	v_and_b32_e32 v130, 3, v123
	v_lshl_add_u32 v130, v128, 4, v130
	v_lshl_add_u32 v130, v129, 2, v130
	v_lshlrev_b32_e32 v130, 11, v130
	v_lshl_add_u32 v130, v124, 3, v130
	v_mov_b32_e32 v131, 0
	s_mul_i32 s5, s19, 0xc80000
	s_lshl_b32 s12, s18, 19
	s_add_u32 s5, s5, s12
	s_lshl_b32 s12, s16, 16
	s_add_u32 s5, s5, s12
	s_lshl_b32 s12, s17, 6
	s_add_u32 s5, s5, s12
	s_add_u32 s5, s5, 0xe7e000
	s_add_u32 s20, s6, s5
	s_addc_u32 s21, s7, 0
	v_lshl_add_u64 v[132:133], s[20:21], 0, v[130:131]
	s_waitcnt vmcnt(24)
	global_load_dwordx4 v[88:91], v[120:121], off offset:192
	global_load_dwordx4 v[92:95], v[120:121], off offset:208
	global_load_dwordx4 v[96:99], v[120:121], off offset:224
	global_load_dwordx4 v[100:103], v[120:121], off offset:240
	global_load_dword v104, v122, s[22:23] offset:-4096
	global_load_dword v105, v122, s[22:23] offset:-2048
	global_load_dword v106, v122, s[22:23]
	global_load_dword v107, v122, s[22:23] offset:2048
	global_load_dword v108, v122, s[24:25] offset:-4096
	global_load_dword v109, v122, s[24:25] offset:-2048
	global_load_dword v110, v122, s[24:25]
	global_load_dword v111, v122, s[24:25] offset:2048
	s_add_u32 s22, s22, 0x4000
	s_addc_u32 s23, s23, 0
	s_add_u32 s24, s24, 0x4000
	s_addc_u32 s25, s25, 0
	v_mfma_f32_32x32x2_f32 v[0:15], v16, v32, v[0:15]
	v_mfma_f32_32x32x2_f32 v[0:15], v18, v33, v[0:15]
	v_mfma_f32_32x32x2_f32 v[0:15], v20, v34, v[0:15]
	v_mfma_f32_32x32x2_f32 v[0:15], v22, v35, v[0:15]
	v_mfma_f32_32x32x2_f32 v[0:15], v24, v36, v[0:15]
	v_mfma_f32_32x32x2_f32 v[0:15], v26, v37, v[0:15]
	v_mfma_f32_32x32x2_f32 v[0:15], v28, v38, v[0:15]
	v_mfma_f32_32x32x2_f32 v[0:15], v30, v39, v[0:15]
	s_waitcnt vmcnt(24)
	global_load_dwordx4 v[16:19], v[120:121], off offset:256
	global_load_dwordx4 v[20:23], v[120:121], off offset:272
	global_load_dwordx4 v[24:27], v[120:121], off offset:288
	global_load_dwordx4 v[28:31], v[120:121], off offset:304
	global_load_dword v32, v122, s[22:23] offset:-4096
	global_load_dword v33, v122, s[22:23] offset:-2048
	global_load_dword v34, v122, s[22:23]
	global_load_dword v35, v122, s[22:23] offset:2048
	global_load_dword v36, v122, s[24:25] offset:-4096
	global_load_dword v37, v122, s[24:25] offset:-2048
	global_load_dword v38, v122, s[24:25]
	global_load_dword v39, v122, s[24:25] offset:2048
	s_add_u32 s22, s22, 0x4000
	s_addc_u32 s23, s23, 0
	s_add_u32 s24, s24, 0x4000
	s_addc_u32 s25, s25, 0
	v_mfma_f32_32x32x2_f32 v[0:15], v40, v56, v[0:15]
	v_mfma_f32_32x32x2_f32 v[0:15], v42, v57, v[0:15]
	v_mfma_f32_32x32x2_f32 v[0:15], v44, v58, v[0:15]
	v_mfma_f32_32x32x2_f32 v[0:15], v46, v59, v[0:15]
	v_mfma_f32_32x32x2_f32 v[0:15], v48, v60, v[0:15]
	v_mfma_f32_32x32x2_f32 v[0:15], v50, v61, v[0:15]
	v_mfma_f32_32x32x2_f32 v[0:15], v52, v62, v[0:15]
	v_mfma_f32_32x32x2_f32 v[0:15], v54, v63, v[0:15]
	s_waitcnt vmcnt(24)
	global_load_dwordx4 v[40:43], v[120:121], off offset:320
	global_load_dwordx4 v[44:47], v[120:121], off offset:336
	global_load_dwordx4 v[48:51], v[120:121], off offset:352
	global_load_dwordx4 v[52:55], v[120:121], off offset:368
	global_load_dword v56, v122, s[22:23] offset:-4096
	global_load_dword v57, v122, s[22:23] offset:-2048
	global_load_dword v58, v122, s[22:23]
	global_load_dword v59, v122, s[22:23] offset:2048
	global_load_dword v60, v122, s[24:25] offset:-4096
	global_load_dword v61, v122, s[24:25] offset:-2048
	global_load_dword v62, v122, s[24:25]
	global_load_dword v63, v122, s[24:25] offset:2048
	s_add_u32 s22, s22, 0x4000
	s_addc_u32 s23, s23, 0
	s_add_u32 s24, s24, 0x4000
	s_addc_u32 s25, s25, 0
	v_mfma_f32_32x32x2_f32 v[0:15], v64, v80, v[0:15]
	v_mfma_f32_32x32x2_f32 v[0:15], v66, v81, v[0:15]
	v_mfma_f32_32x32x2_f32 v[0:15], v68, v82, v[0:15]
	v_mfma_f32_32x32x2_f32 v[0:15], v70, v83, v[0:15]
	v_mfma_f32_32x32x2_f32 v[0:15], v72, v84, v[0:15]
	v_mfma_f32_32x32x2_f32 v[0:15], v74, v85, v[0:15]
	v_mfma_f32_32x32x2_f32 v[0:15], v76, v86, v[0:15]
	v_mfma_f32_32x32x2_f32 v[0:15], v78, v87, v[0:15]
	s_waitcnt vmcnt(24)
	global_load_dwordx4 v[64:67], v[120:121], off offset:384
	global_load_dwordx4 v[68:71], v[120:121], off offset:400
	global_load_dwordx4 v[72:75], v[120:121], off offset:416
	global_load_dwordx4 v[76:79], v[120:121], off offset:432
	global_load_dword v80, v122, s[22:23] offset:-4096
	global_load_dword v81, v122, s[22:23] offset:-2048
	global_load_dword v82, v122, s[22:23]
	global_load_dword v83, v122, s[22:23] offset:2048
	global_load_dword v84, v122, s[24:25] offset:-4096
	global_load_dword v85, v122, s[24:25] offset:-2048
	global_load_dword v86, v122, s[24:25]
	global_load_dword v87, v122, s[24:25] offset:2048
	s_add_u32 s22, s22, 0x4000
	s_addc_u32 s23, s23, 0
	s_add_u32 s24, s24, 0x4000
	s_addc_u32 s25, s25, 0
	v_mfma_f32_32x32x2_f32 v[0:15], v88, v104, v[0:15]
	v_mfma_f32_32x32x2_f32 v[0:15], v90, v105, v[0:15]
	v_mfma_f32_32x32x2_f32 v[0:15], v92, v106, v[0:15]
	v_mfma_f32_32x32x2_f32 v[0:15], v94, v107, v[0:15]
	v_mfma_f32_32x32x2_f32 v[0:15], v96, v108, v[0:15]
	v_mfma_f32_32x32x2_f32 v[0:15], v98, v109, v[0:15]
	v_mfma_f32_32x32x2_f32 v[0:15], v100, v110, v[0:15]
	v_mfma_f32_32x32x2_f32 v[0:15], v102, v111, v[0:15]
	s_waitcnt vmcnt(24)
	global_load_dwordx4 v[88:91], v[120:121], off offset:448
	global_load_dwordx4 v[92:95], v[120:121], off offset:464
	global_load_dwordx4 v[96:99], v[120:121], off offset:480
	global_load_dwordx4 v[100:103], v[120:121], off offset:496
	global_load_dword v104, v122, s[22:23] offset:-4096
	global_load_dword v105, v122, s[22:23] offset:-2048
	global_load_dword v106, v122, s[22:23]
	global_load_dword v107, v122, s[22:23] offset:2048
	global_load_dword v108, v122, s[24:25] offset:-4096
	global_load_dword v109, v122, s[24:25] offset:-2048
	global_load_dword v110, v122, s[24:25]
	global_load_dword v111, v122, s[24:25] offset:2048
	s_add_u32 s22, s22, 0x4000
	s_addc_u32 s23, s23, 0
	s_add_u32 s24, s24, 0x4000
	s_addc_u32 s25, s25, 0
	v_mfma_f32_32x32x2_f32 v[0:15], v16, v32, v[0:15]
	v_mfma_f32_32x32x2_f32 v[0:15], v18, v33, v[0:15]
	v_mfma_f32_32x32x2_f32 v[0:15], v20, v34, v[0:15]
	v_mfma_f32_32x32x2_f32 v[0:15], v22, v35, v[0:15]
	v_mfma_f32_32x32x2_f32 v[0:15], v24, v36, v[0:15]
	v_mfma_f32_32x32x2_f32 v[0:15], v26, v37, v[0:15]
	v_mfma_f32_32x32x2_f32 v[0:15], v28, v38, v[0:15]
	v_mfma_f32_32x32x2_f32 v[0:15], v30, v39, v[0:15]
	s_waitcnt vmcnt(24)
	global_load_dwordx4 v[16:19], v[120:121], off offset:512
	global_load_dwordx4 v[20:23], v[120:121], off offset:528
	global_load_dwordx4 v[24:27], v[120:121], off offset:544
	global_load_dwordx4 v[28:31], v[120:121], off offset:560
	global_load_dword v32, v122, s[22:23] offset:-4096
	global_load_dword v33, v122, s[22:23] offset:-2048
	global_load_dword v34, v122, s[22:23]
	global_load_dword v35, v122, s[22:23] offset:2048
	global_load_dword v36, v122, s[24:25] offset:-4096
	global_load_dword v37, v122, s[24:25] offset:-2048
	global_load_dword v38, v122, s[24:25]
	global_load_dword v39, v122, s[24:25] offset:2048
	s_add_u32 s22, s22, 0x4000
	s_addc_u32 s23, s23, 0
	s_add_u32 s24, s24, 0x4000
	s_addc_u32 s25, s25, 0
	v_mfma_f32_32x32x2_f32 v[0:15], v40, v56, v[0:15]
	v_mfma_f32_32x32x2_f32 v[0:15], v42, v57, v[0:15]
	v_mfma_f32_32x32x2_f32 v[0:15], v44, v58, v[0:15]
	v_mfma_f32_32x32x2_f32 v[0:15], v46, v59, v[0:15]
	v_mfma_f32_32x32x2_f32 v[0:15], v48, v60, v[0:15]
	v_mfma_f32_32x32x2_f32 v[0:15], v50, v61, v[0:15]
	v_mfma_f32_32x32x2_f32 v[0:15], v52, v62, v[0:15]
	v_mfma_f32_32x32x2_f32 v[0:15], v54, v63, v[0:15]
	s_waitcnt vmcnt(24)
	global_load_dwordx4 v[40:43], v[120:121], off offset:576
	global_load_dwordx4 v[44:47], v[120:121], off offset:592
	global_load_dwordx4 v[48:51], v[120:121], off offset:608
	global_load_dwordx4 v[52:55], v[120:121], off offset:624
	global_load_dword v56, v122, s[22:23] offset:-4096
	global_load_dword v57, v122, s[22:23] offset:-2048
	global_load_dword v58, v122, s[22:23]
	global_load_dword v59, v122, s[22:23] offset:2048
	global_load_dword v60, v122, s[24:25] offset:-4096
	global_load_dword v61, v122, s[24:25] offset:-2048
	global_load_dword v62, v122, s[24:25]
	global_load_dword v63, v122, s[24:25] offset:2048
	s_add_u32 s22, s22, 0x4000
	s_addc_u32 s23, s23, 0
	s_add_u32 s24, s24, 0x4000
	s_addc_u32 s25, s25, 0
	v_mfma_f32_32x32x2_f32 v[0:15], v64, v80, v[0:15]
	v_mfma_f32_32x32x2_f32 v[0:15], v66, v81, v[0:15]
	v_mfma_f32_32x32x2_f32 v[0:15], v68, v82, v[0:15]
	v_mfma_f32_32x32x2_f32 v[0:15], v70, v83, v[0:15]
	v_mfma_f32_32x32x2_f32 v[0:15], v72, v84, v[0:15]
	v_mfma_f32_32x32x2_f32 v[0:15], v74, v85, v[0:15]
	v_mfma_f32_32x32x2_f32 v[0:15], v76, v86, v[0:15]
	v_mfma_f32_32x32x2_f32 v[0:15], v78, v87, v[0:15]
	s_waitcnt vmcnt(24)
	global_load_dwordx4 v[64:67], v[120:121], off offset:640
	global_load_dwordx4 v[68:71], v[120:121], off offset:656
	global_load_dwordx4 v[72:75], v[120:121], off offset:672
	global_load_dwordx4 v[76:79], v[120:121], off offset:688
	global_load_dword v80, v122, s[22:23] offset:-4096
	global_load_dword v81, v122, s[22:23] offset:-2048
	global_load_dword v82, v122, s[22:23]
	global_load_dword v83, v122, s[22:23] offset:2048
	global_load_dword v84, v122, s[24:25] offset:-4096
	global_load_dword v85, v122, s[24:25] offset:-2048
	global_load_dword v86, v122, s[24:25]
	global_load_dword v87, v122, s[24:25] offset:2048
	s_add_u32 s22, s22, 0x4000
	s_addc_u32 s23, s23, 0
	s_add_u32 s24, s24, 0x4000
	s_addc_u32 s25, s25, 0
	v_mfma_f32_32x32x2_f32 v[0:15], v88, v104, v[0:15]
	v_mfma_f32_32x32x2_f32 v[0:15], v90, v105, v[0:15]
	v_mfma_f32_32x32x2_f32 v[0:15], v92, v106, v[0:15]
	v_mfma_f32_32x32x2_f32 v[0:15], v94, v107, v[0:15]
	v_mfma_f32_32x32x2_f32 v[0:15], v96, v108, v[0:15]
	v_mfma_f32_32x32x2_f32 v[0:15], v98, v109, v[0:15]
	v_mfma_f32_32x32x2_f32 v[0:15], v100, v110, v[0:15]
	v_mfma_f32_32x32x2_f32 v[0:15], v102, v111, v[0:15]
	s_waitcnt vmcnt(24)
	global_load_dwordx4 v[88:91], v[120:121], off offset:704
	global_load_dwordx4 v[92:95], v[120:121], off offset:720
	global_load_dwordx4 v[96:99], v[120:121], off offset:736
	global_load_dwordx4 v[100:103], v[120:121], off offset:752
	global_load_dword v104, v122, s[22:23] offset:-4096
	global_load_dword v105, v122, s[22:23] offset:-2048
	global_load_dword v106, v122, s[22:23]
	global_load_dword v107, v122, s[22:23] offset:2048
	global_load_dword v108, v122, s[24:25] offset:-4096
	global_load_dword v109, v122, s[24:25] offset:-2048
	global_load_dword v110, v122, s[24:25]
	global_load_dword v111, v122, s[24:25] offset:2048
	s_add_u32 s22, s22, 0x4000
	s_addc_u32 s23, s23, 0
	s_add_u32 s24, s24, 0x4000
	s_addc_u32 s25, s25, 0
	v_mfma_f32_32x32x2_f32 v[0:15], v16, v32, v[0:15]
	v_mfma_f32_32x32x2_f32 v[0:15], v18, v33, v[0:15]
	v_mfma_f32_32x32x2_f32 v[0:15], v20, v34, v[0:15]
	v_mfma_f32_32x32x2_f32 v[0:15], v22, v35, v[0:15]
	v_mfma_f32_32x32x2_f32 v[0:15], v24, v36, v[0:15]
	v_mfma_f32_32x32x2_f32 v[0:15], v26, v37, v[0:15]
	v_mfma_f32_32x32x2_f32 v[0:15], v28, v38, v[0:15]
	v_mfma_f32_32x32x2_f32 v[0:15], v30, v39, v[0:15]
	s_waitcnt vmcnt(24)
	global_load_dwordx4 v[16:19], v[120:121], off offset:768
	global_load_dwordx4 v[20:23], v[120:121], off offset:784
	global_load_dwordx4 v[24:27], v[120:121], off offset:800
	global_load_dwordx4 v[28:31], v[120:121], off offset:816
	global_load_dword v32, v122, s[22:23] offset:-4096
	global_load_dword v33, v122, s[22:23] offset:-2048
	global_load_dword v34, v122, s[22:23]
	global_load_dword v35, v122, s[22:23] offset:2048
	global_load_dword v36, v122, s[24:25] offset:-4096
	global_load_dword v37, v122, s[24:25] offset:-2048
	global_load_dword v38, v122, s[24:25]
	global_load_dword v39, v122, s[24:25] offset:2048
	s_add_u32 s22, s22, 0x4000
	s_addc_u32 s23, s23, 0
	s_add_u32 s24, s24, 0x4000
	s_addc_u32 s25, s25, 0
	v_mfma_f32_32x32x2_f32 v[0:15], v40, v56, v[0:15]
	v_mfma_f32_32x32x2_f32 v[0:15], v42, v57, v[0:15]
	v_mfma_f32_32x32x2_f32 v[0:15], v44, v58, v[0:15]
	v_mfma_f32_32x32x2_f32 v[0:15], v46, v59, v[0:15]
	v_mfma_f32_32x32x2_f32 v[0:15], v48, v60, v[0:15]
	v_mfma_f32_32x32x2_f32 v[0:15], v50, v61, v[0:15]
	v_mfma_f32_32x32x2_f32 v[0:15], v52, v62, v[0:15]
	v_mfma_f32_32x32x2_f32 v[0:15], v54, v63, v[0:15]
	s_waitcnt vmcnt(24)
	global_load_dwordx4 v[40:43], v[120:121], off offset:832
	global_load_dwordx4 v[44:47], v[120:121], off offset:848
	global_load_dwordx4 v[48:51], v[120:121], off offset:864
	global_load_dwordx4 v[52:55], v[120:121], off offset:880
	global_load_dword v56, v122, s[22:23] offset:-4096
	global_load_dword v57, v122, s[22:23] offset:-2048
	global_load_dword v58, v122, s[22:23]
	global_load_dword v59, v122, s[22:23] offset:2048
	global_load_dword v60, v122, s[24:25] offset:-4096
	global_load_dword v61, v122, s[24:25] offset:-2048
	global_load_dword v62, v122, s[24:25]
	global_load_dword v63, v122, s[24:25] offset:2048
	s_add_u32 s22, s22, 0x4000
	s_addc_u32 s23, s23, 0
	s_add_u32 s24, s24, 0x4000
	s_addc_u32 s25, s25, 0
	v_mfma_f32_32x32x2_f32 v[0:15], v64, v80, v[0:15]
	v_mfma_f32_32x32x2_f32 v[0:15], v66, v81, v[0:15]
	v_mfma_f32_32x32x2_f32 v[0:15], v68, v82, v[0:15]
	v_mfma_f32_32x32x2_f32 v[0:15], v70, v83, v[0:15]
	v_mfma_f32_32x32x2_f32 v[0:15], v72, v84, v[0:15]
	v_mfma_f32_32x32x2_f32 v[0:15], v74, v85, v[0:15]
	v_mfma_f32_32x32x2_f32 v[0:15], v76, v86, v[0:15]
	v_mfma_f32_32x32x2_f32 v[0:15], v78, v87, v[0:15]
	s_waitcnt vmcnt(24)
	global_load_dwordx4 v[64:67], v[120:121], off offset:896
	global_load_dwordx4 v[68:71], v[120:121], off offset:912
	global_load_dwordx4 v[72:75], v[120:121], off offset:928
	global_load_dwordx4 v[76:79], v[120:121], off offset:944
	global_load_dword v80, v122, s[22:23] offset:-4096
	global_load_dword v81, v122, s[22:23] offset:-2048
	global_load_dword v82, v122, s[22:23]
	global_load_dword v83, v122, s[22:23] offset:2048
	global_load_dword v84, v122, s[24:25] offset:-4096
	global_load_dword v85, v122, s[24:25] offset:-2048
	global_load_dword v86, v122, s[24:25]
	global_load_dword v87, v122, s[24:25] offset:2048
	s_add_u32 s22, s22, 0x4000
	s_addc_u32 s23, s23, 0
	s_add_u32 s24, s24, 0x4000
	s_addc_u32 s25, s25, 0
	v_mfma_f32_32x32x2_f32 v[0:15], v88, v104, v[0:15]
	v_mfma_f32_32x32x2_f32 v[0:15], v90, v105, v[0:15]
	v_mfma_f32_32x32x2_f32 v[0:15], v92, v106, v[0:15]
	v_mfma_f32_32x32x2_f32 v[0:15], v94, v107, v[0:15]
	v_mfma_f32_32x32x2_f32 v[0:15], v96, v108, v[0:15]
	v_mfma_f32_32x32x2_f32 v[0:15], v98, v109, v[0:15]
	v_mfma_f32_32x32x2_f32 v[0:15], v100, v110, v[0:15]
	v_mfma_f32_32x32x2_f32 v[0:15], v102, v111, v[0:15]
	s_waitcnt vmcnt(24)
	global_load_dwordx4 v[88:91], v[120:121], off offset:960
	global_load_dwordx4 v[92:95], v[120:121], off offset:976
	global_load_dwordx4 v[96:99], v[120:121], off offset:992
	global_load_dwordx4 v[100:103], v[120:121], off offset:1008
	global_load_dword v104, v122, s[22:23] offset:-4096
	global_load_dword v105, v122, s[22:23] offset:-2048
	global_load_dword v106, v122, s[22:23]
	global_load_dword v107, v122, s[22:23] offset:2048
	global_load_dword v108, v122, s[24:25] offset:-4096
	global_load_dword v109, v122, s[24:25] offset:-2048
	global_load_dword v110, v122, s[24:25]
	global_load_dword v111, v122, s[24:25] offset:2048
	s_add_u32 s22, s22, 0x4000
	s_addc_u32 s23, s23, 0
	s_add_u32 s24, s24, 0x4000
	s_addc_u32 s25, s25, 0
	v_mfma_f32_32x32x2_f32 v[0:15], v16, v32, v[0:15]
	v_mfma_f32_32x32x2_f32 v[0:15], v18, v33, v[0:15]
	v_mfma_f32_32x32x2_f32 v[0:15], v20, v34, v[0:15]
	v_mfma_f32_32x32x2_f32 v[0:15], v22, v35, v[0:15]
	v_mfma_f32_32x32x2_f32 v[0:15], v24, v36, v[0:15]
	v_mfma_f32_32x32x2_f32 v[0:15], v26, v37, v[0:15]
	v_mfma_f32_32x32x2_f32 v[0:15], v28, v38, v[0:15]
	v_mfma_f32_32x32x2_f32 v[0:15], v30, v39, v[0:15]
	s_waitcnt vmcnt(24)
	v_mfma_f32_32x32x2_f32 v[0:15], v40, v56, v[0:15]
	v_mfma_f32_32x32x2_f32 v[0:15], v42, v57, v[0:15]
	v_mfma_f32_32x32x2_f32 v[0:15], v44, v58, v[0:15]
	v_mfma_f32_32x32x2_f32 v[0:15], v46, v59, v[0:15]
	v_mfma_f32_32x32x2_f32 v[0:15], v48, v60, v[0:15]
	v_mfma_f32_32x32x2_f32 v[0:15], v50, v61, v[0:15]
	v_mfma_f32_32x32x2_f32 v[0:15], v52, v62, v[0:15]
	v_mfma_f32_32x32x2_f32 v[0:15], v54, v63, v[0:15]
	s_waitcnt vmcnt(12)
	v_mfma_f32_32x32x2_f32 v[0:15], v64, v80, v[0:15]
	v_mfma_f32_32x32x2_f32 v[0:15], v66, v81, v[0:15]
	v_mfma_f32_32x32x2_f32 v[0:15], v68, v82, v[0:15]
	v_mfma_f32_32x32x2_f32 v[0:15], v70, v83, v[0:15]
	v_mfma_f32_32x32x2_f32 v[0:15], v72, v84, v[0:15]
	v_mfma_f32_32x32x2_f32 v[0:15], v74, v85, v[0:15]
	v_mfma_f32_32x32x2_f32 v[0:15], v76, v86, v[0:15]
	v_mfma_f32_32x32x2_f32 v[0:15], v78, v87, v[0:15]
	s_waitcnt vmcnt(0)
	v_mfma_f32_32x32x2_f32 v[0:15], v88, v104, v[0:15]
	v_mfma_f32_32x32x2_f32 v[0:15], v90, v105, v[0:15]
	v_mfma_f32_32x32x2_f32 v[0:15], v92, v106, v[0:15]
	v_mfma_f32_32x32x2_f32 v[0:15], v94, v107, v[0:15]
	v_mfma_f32_32x32x2_f32 v[0:15], v96, v108, v[0:15]
	v_mfma_f32_32x32x2_f32 v[0:15], v98, v109, v[0:15]
	v_mfma_f32_32x32x2_f32 v[0:15], v100, v110, v[0:15]
	v_mfma_f32_32x32x2_f32 v[0:15], v102, v111, v[0:15]
	s_nop 7
	s_nop 7
	s_nop 7
	v_cvt_pk_bf16_f32 v16, v0, v1
	v_cvt_pk_bf16_f32 v17, v2, v3
	v_cvt_pk_bf16_f32 v18, v4, v5
	v_cvt_pk_bf16_f32 v19, v6, v7
	v_cvt_pk_bf16_f32 v20, v8, v9
	v_cvt_pk_bf16_f32 v21, v10, v11
	v_cvt_pk_bf16_f32 v22, v12, v13
	v_cvt_pk_bf16_f32 v23, v14, v15
	global_store_dwordx2 v[132:133], v[16:17], off
	global_store_dwordx2 v[132:133], v[18:19], off offset:16
	global_store_dwordx2 v[132:133], v[20:21], off offset:32
	global_store_dwordx2 v[132:133], v[22:23], off offset:48
.LBB0_179:
	v_readlane_b32 s4, v255, 62
	s_nop 3
	s_cmp_eq_u32 s4, 2
	s_cbranch_scc1 .LBB0_193
	v_readlane_b32 s4, v253, 2
	v_readlane_b32 s5, v253, 3
	s_andn2_b64 vcc, exec, s[4:5]
	s_cbranch_vccnz .Lp1_after_norm
	v_mov_b32_e32 v0, v195
	s_mul_i32 s4, s2, s89
	s_nop 0
	v_add_u32_e32 v1, s4, v0
	s_nop 0
	v_readfirstlane_b32 s4, v1
	s_cmp_gt_u32 s4, 0xbffff
	s_cbranch_scc1 .Lp1_after_norm
	v_mbcnt_lo_u32_b32 v1, -1, 0
	v_mbcnt_hi_u32_b32 v1, -1, v1
	v_and_b32_e32 v2, 64, v1
	v_add_u32_e32 v2, 64, v2
	v_xor_b32_e32 v3, 32, v1
	v_cmp_lt_i32_e32 vcc, v3, v2
	s_lshr_b32 s17, s66, 6
	s_waitcnt lgkmcnt(0)
	s_add_u32 s39, s6, 0x1e0000
	v_cndmask_b32_e32 v3, v1, v3, vcc
	v_lshlrev_b32_e32 v103, 2, v3
	v_xor_b32_e32 v3, 16, v1
	v_cmp_lt_i32_e32 vcc, v3, v2
	s_addc_u32 s40, s7, 0
	s_lshr_b32 s41, s4, 6
	v_cndmask_b32_e32 v3, v1, v3, vcc
	v_lshlrev_b32_e32 v108, 2, v3
	v_xor_b32_e32 v3, 8, v1
	v_cmp_lt_i32_e32 vcc, v3, v2
	s_load_dwordx2 s[4:5], s[8:9], 0x30
	v_lshlrev_b32_e32 v0, 2, v0
	v_cndmask_b32_e32 v3, v1, v3, vcc
	v_lshlrev_b32_e32 v109, 2, v3
	v_xor_b32_e32 v3, 4, v1
	v_cmp_lt_i32_e32 vcc, v3, v2
	v_and_b32_e32 v0, 0xfc, v0
	v_mov_b32_e32 v97, 0
	v_cndmask_b32_e32 v3, v1, v3, vcc
	v_lshlrev_b32_e32 v110, 2, v3
	v_xor_b32_e32 v3, 2, v1
	v_cmp_lt_i32_e32 vcc, v3, v2
	v_lshlrev_b32_e32 v96, 2, v0
	s_waitcnt lgkmcnt(0)
	v_lshl_add_u64 v[98:99], s[4:5], 0, v[96:97]
	v_cndmask_b32_e32 v3, v1, v3, vcc
	v_lshlrev_b32_e32 v111, 2, v3
	v_xor_b32_e32 v3, 1, v1
	v_cmp_lt_i32_e32 vcc, v3, v2
	v_lshlrev_b32_e32 v96, 1, v0
	v_or_b32_e32 v2, 0x100, v0
	v_cndmask_b32_e32 v1, v1, v3, vcc
	v_or_b32_e32 v4, 0x200, v0
	v_or_b32_e32 v6, 0x300, v0
	v_lshl_add_u64 v[8:9], s[6:7], 0, v[96:97]
	s_mov_b64 s[4:5], 0x39fe000
	s_mul_i32 s38, s17, 6
	s_mov_b32 s13, 0
	v_lshlrev_b32_e32 v112, 2, v1
	v_lshl_add_u64 v[100:101], v[8:9], 0, s[4:5]
	s_lshl_b32 s14, s41, 10
	s_mul_i32 s42, s17, 0x1800
	s_lshl_b32 s43, s17, 1
	s_lshl_b32 s44, s17, 11
	s_mul_i32 s45, s17, 3
	s_mul_i32 s46, s17, 0xc00
	s_lshl_b32 s47, s17, 2
	s_lshl_b32 s48, s17, 12
	s_mul_i32 s49, s17, 5
	s_mul_i32 s50, s17, 0x1400
	s_lshl_b32 s51, s17, 10
	v_mov_b32_e32 v113, 0x1000
	v_lshlrev_b32_e32 v114, 2, v0
	s_mov_b32 s16, 0x3a800000
	v_mov_b32_e32 v102, 0x358637bd
	s_mov_b32 s52, 0x800000
	v_lshlrev_b32_e32 v115, 2, v2
	v_lshlrev_b32_e32 v116, 2, v4
	v_lshlrev_b32_e32 v117, 2, v6
	s_load_dwordx2 s[18:19], s[8:9], 0x0
	s_load_dwordx2 s[20:21], s[8:9], 0x8
	s_lshl_b32 s12, s41, 12
	s_lshl_b32 s15, s41, 11
	s_add_u32 s46, s6, 0x39fe000
	s_addc_u32 s47, s7, 0
	s_add_u32 s46, s46, s15
	s_addc_u32 s47, s47, 0
	global_load_dwordx4 v[144:147], v[98:99], off
	global_load_dwordx4 v[148:151], v[98:99], off offset:1024
	global_load_dwordx4 v[152:155], v[98:99], off offset:2048
	global_load_dwordx4 v[156:159], v[98:99], off offset:3072
	s_waitcnt lgkmcnt(0)
	s_add_u32 s24, s18, s12
	s_addc_u32 s25, s19, 0
	s_add_u32 s26, s24, 0x800000
	s_addc_u32 s27, s25, 0
	s_add_u32 s28, s20, s12
	s_addc_u32 s29, s21, 0
	s_add_u32 s30, s28, 0x800000
	s_addc_u32 s31, s29, 0
	s_add_u32 s34, s30, 0x800000
	s_addc_u32 s35, s31, 0
	s_add_u32 s36, s34, 0x800000
	s_addc_u32 s37, s35, 0
	global_load_dwordx4 v[0:3], v114, s[24:25] nt
	global_load_dwordx4 v[4:7], v114, s[24:25] offset:1024 nt
	global_load_dwordx4 v[8:11], v114, s[24:25] offset:2048 nt
	global_load_dwordx4 v[12:15], v114, s[24:25] offset:3072 nt
	global_load_dwordx4 v[16:19], v114, s[26:27] nt
	global_load_dwordx4 v[20:23], v114, s[26:27] offset:1024 nt
	global_load_dwordx4 v[24:27], v114, s[26:27] offset:2048 nt
	global_load_dwordx4 v[28:31], v114, s[26:27] offset:3072 nt
	global_load_dwordx4 v[32:35], v114, s[28:29] nt
	global_load_dwordx4 v[36:39], v114, s[28:29] offset:1024 nt
	global_load_dwordx4 v[40:43], v114, s[28:29] offset:2048 nt
	global_load_dwordx4 v[44:47], v114, s[28:29] offset:3072 nt
	global_load_dwordx4 v[48:51], v114, s[30:31] nt
	global_load_dwordx4 v[52:55], v114, s[30:31] offset:1024 nt
	global_load_dwordx4 v[56:59], v114, s[30:31] offset:2048 nt
	global_load_dwordx4 v[60:63], v114, s[30:31] offset:3072 nt
	global_load_dwordx4 v[64:67], v114, s[34:35] nt
	global_load_dwordx4 v[68:71], v114, s[34:35] offset:1024 nt
	global_load_dwordx4 v[72:75], v114, s[34:35] offset:2048 nt
	global_load_dwordx4 v[76:79], v114, s[34:35] offset:3072 nt
	global_load_dwordx4 v[80:83], v114, s[36:37] nt
	global_load_dwordx4 v[84:87], v114, s[36:37] offset:1024 nt
	global_load_dwordx4 v[88:91], v114, s[36:37] offset:2048 nt
	global_load_dwordx4 v[92:95], v114, s[36:37] offset:3072 nt
	s_add_u32 s48, s39, 0x0
	s_addc_u32 s49, s40, 0
	s_add_u32 s50, s48, 0x1000
	s_addc_u32 s51, s49, 0
	global_load_dwordx4 v[160:163], v114, s[50:51]
	global_load_dwordx4 v[164:167], v114, s[50:51] offset:1024
	global_load_dwordx4 v[168:171], v114, s[50:51] offset:2048
	global_load_dwordx4 v[172:175], v114, s[50:51] offset:3072
	global_load_dwordx4 v[176:179], v114, s[48:49]
	global_load_dwordx4 v[180:183], v114, s[48:49] offset:1024
	global_load_dwordx4 v[184:187], v114, s[48:49] offset:2048
	global_load_dwordx4 v[188:191], v114, s[48:49] offset:3072
	s_add_u32 s48, s39, 0x3000
	s_addc_u32 s49, s40, 0
	s_add_u32 s50, s48, 0x1000
	s_addc_u32 s51, s49, 0
	global_load_dwordx4 v[196:199], v114, s[50:51]
	global_load_dwordx4 v[200:203], v114, s[50:51] offset:1024
	global_load_dwordx4 v[204:207], v114, s[50:51] offset:2048
	global_load_dwordx4 v[208:211], v114, s[50:51] offset:3072
	global_load_dwordx4 v[212:215], v114, s[48:49]
	global_load_dwordx4 v[216:219], v114, s[48:49] offset:1024
	global_load_dwordx4 v[220:223], v114, s[48:49] offset:2048
	global_load_dwordx4 v[224:227], v114, s[48:49] offset:3072
	s_add_u32 s48, s39, 0x6000
	s_addc_u32 s49, s40, 0
	s_add_u32 s50, s48, 0x1000
	s_addc_u32 s51, s49, 0
	global_load_dwordx4 v[228:231], v114, s[50:51]
	global_load_dwordx4 v[232:235], v114, s[50:51] offset:1024
	global_load_dwordx4 v[236:239], v114, s[50:51] offset:2048
	global_load_dwordx4 v[240:243], v114, s[50:51] offset:3072
	global_load_dwordx4 v[244:247], v114, s[48:49]
	global_load_dwordx4 v[248:251], v114, s[48:49] offset:1024
	global_load_dwordx4 v[118:121], v114, s[48:49] offset:2048
	global_load_dwordx4 v[122:125], v114, s[48:49] offset:3072
	s_waitcnt vmcnt(47)
	v_mul_f32_e32 v132, v1, v1
	v_fmac_f32_e32 v132, v0, v0
	v_fmac_f32_e32 v132, v2, v2
	v_fmac_f32_e32 v132, v3, v3
	s_waitcnt vmcnt(46)
	v_mul_f32_e32 v133, v5, v5
	v_fmac_f32_e32 v133, v4, v4
	v_fmac_f32_e32 v133, v6, v6
	v_fmac_f32_e32 v133, v7, v7
	s_waitcnt vmcnt(45)
	v_mul_f32_e32 v134, v9, v9
	v_fmac_f32_e32 v134, v8, v8
	v_fmac_f32_e32 v134, v10, v10
	v_fmac_f32_e32 v134, v11, v11
	s_waitcnt vmcnt(44)
	v_mul_f32_e32 v135, v13, v13
	v_fmac_f32_e32 v135, v12, v12
	v_fmac_f32_e32 v135, v14, v14
	v_fmac_f32_e32 v135, v15, v15
	v_add_f32_e32 v126, v132, v133
	v_add_f32_e32 v126, v126, v134
	v_add_f32_e32 v126, v126, v135
	s_waitcnt vmcnt(43)
	v_mul_f32_e32 v132, v17, v17
	v_fmac_f32_e32 v132, v16, v16
	v_fmac_f32_e32 v132, v18, v18
	v_fmac_f32_e32 v132, v19, v19
	s_waitcnt vmcnt(42)
	v_mul_f32_e32 v133, v21, v21
	v_fmac_f32_e32 v133, v20, v20
	v_fmac_f32_e32 v133, v22, v22
	v_fmac_f32_e32 v133, v23, v23
	s_waitcnt vmcnt(41)
	v_mul_f32_e32 v134, v25, v25
	v_fmac_f32_e32 v134, v24, v24
	v_fmac_f32_e32 v134, v26, v26
	v_fmac_f32_e32 v134, v27, v27
	s_waitcnt vmcnt(40)
	v_mul_f32_e32 v135, v29, v29
	v_fmac_f32_e32 v135, v28, v28
	v_fmac_f32_e32 v135, v30, v30
	v_fmac_f32_e32 v135, v31, v31
	v_add_f32_e32 v127, v132, v133
	v_add_f32_e32 v127, v127, v134
	v_add_f32_e32 v127, v127, v135
	s_waitcnt vmcnt(39)
	v_mul_f32_e32 v132, v33, v33
	v_fmac_f32_e32 v132, v32, v32
	v_fmac_f32_e32 v132, v34, v34
	v_fmac_f32_e32 v132, v35, v35
	s_waitcnt vmcnt(38)
	v_mul_f32_e32 v133, v37, v37
	v_fmac_f32_e32 v133, v36, v36
	v_fmac_f32_e32 v133, v38, v38
	v_fmac_f32_e32 v133, v39, v39
	s_waitcnt vmcnt(37)
	v_mul_f32_e32 v134, v41, v41
	v_fmac_f32_e32 v134, v40, v40
	v_fmac_f32_e32 v134, v42, v42
	v_fmac_f32_e32 v134, v43, v43
	s_waitcnt vmcnt(36)
	v_mul_f32_e32 v135, v45, v45
	v_fmac_f32_e32 v135, v44, v44
	v_fmac_f32_e32 v135, v46, v46
	v_fmac_f32_e32 v135, v47, v47
	v_add_f32_e32 v128, v132, v133
	v_add_f32_e32 v128, v128, v134
	v_add_f32_e32 v128, v128, v135
	s_waitcnt vmcnt(35)
	v_mul_f32_e32 v132, v49, v49
	v_fmac_f32_e32 v132, v48, v48
	v_fmac_f32_e32 v132, v50, v50
	v_fmac_f32_e32 v132, v51, v51
	s_waitcnt vmcnt(34)
	v_mul_f32_e32 v133, v53, v53
	v_fmac_f32_e32 v133, v52, v52
	v_fmac_f32_e32 v133, v54, v54
	v_fmac_f32_e32 v133, v55, v55
	s_waitcnt vmcnt(33)
	v_mul_f32_e32 v134, v57, v57
	v_fmac_f32_e32 v134, v56, v56
	v_fmac_f32_e32 v134, v58, v58
	v_fmac_f32_e32 v134, v59, v59
	s_waitcnt vmcnt(32)
	v_mul_f32_e32 v135, v61, v61
	v_fmac_f32_e32 v135, v60, v60
	v_fmac_f32_e32 v135, v62, v62
	v_fmac_f32_e32 v135, v63, v63
	v_add_f32_e32 v129, v132, v133
	v_add_f32_e32 v129, v129, v134
	v_add_f32_e32 v129, v129, v135
	s_waitcnt vmcnt(31)
	v_mul_f32_e32 v132, v65, v65
	v_fmac_f32_e32 v132, v64, v64
	v_fmac_f32_e32 v132, v66, v66
	v_fmac_f32_e32 v132, v67, v67
	s_waitcnt vmcnt(30)
	v_mul_f32_e32 v133, v69, v69
	v_fmac_f32_e32 v133, v68, v68
	v_fmac_f32_e32 v133, v70, v70
	v_fmac_f32_e32 v133, v71, v71
	s_waitcnt vmcnt(29)
	v_mul_f32_e32 v134, v73, v73
	v_fmac_f32_e32 v134, v72, v72
	v_fmac_f32_e32 v134, v74, v74
	v_fmac_f32_e32 v134, v75, v75
	s_waitcnt vmcnt(28)
	v_mul_f32_e32 v135, v77, v77
	v_fmac_f32_e32 v135, v76, v76
	v_fmac_f32_e32 v135, v78, v78
	v_fmac_f32_e32 v135, v79, v79
	v_add_f32_e32 v130, v132, v133
	v_add_f32_e32 v130, v130, v134
	v_add_f32_e32 v130, v130, v135
	s_waitcnt vmcnt(27)
	v_mul_f32_e32 v132, v81, v81
	v_fmac_f32_e32 v132, v80, v80
	v_fmac_f32_e32 v132, v82, v82
	v_fmac_f32_e32 v132, v83, v83
	s_waitcnt vmcnt(26)
	v_mul_f32_e32 v133, v85, v85
	v_fmac_f32_e32 v133, v84, v84
	v_fmac_f32_e32 v133, v86, v86
	v_fmac_f32_e32 v133, v87, v87
	s_waitcnt vmcnt(25)
	v_mul_f32_e32 v134, v89, v89
	v_fmac_f32_e32 v134, v88, v88
	v_fmac_f32_e32 v134, v90, v90
	v_fmac_f32_e32 v134, v91, v91
	s_waitcnt vmcnt(24)
	v_mul_f32_e32 v135, v93, v93
	v_fmac_f32_e32 v135, v92, v92
	v_fmac_f32_e32 v135, v94, v94
	v_fmac_f32_e32 v135, v95, v95
	v_add_f32_e32 v131, v132, v133
	v_add_f32_e32 v131, v131, v134
	v_add_f32_e32 v131, v131, v135
	ds_bpermute_b32 v136, v103, v126
	ds_bpermute_b32 v137, v103, v127
	ds_bpermute_b32 v138, v103, v128
	ds_bpermute_b32 v139, v103, v129
	ds_bpermute_b32 v140, v103, v130
	ds_bpermute_b32 v141, v103, v131
	s_waitcnt lgkmcnt(5)
	v_add_f32_e32 v126, v126, v136
	s_waitcnt lgkmcnt(4)
	v_add_f32_e32 v127, v127, v137
	s_waitcnt lgkmcnt(3)
	v_add_f32_e32 v128, v128, v138
	s_waitcnt lgkmcnt(2)
	v_add_f32_e32 v129, v129, v139
	s_waitcnt lgkmcnt(1)
	v_add_f32_e32 v130, v130, v140
	s_waitcnt lgkmcnt(0)
	v_add_f32_e32 v131, v131, v141
	ds_bpermute_b32 v136, v108, v126
	ds_bpermute_b32 v137, v108, v127
	ds_bpermute_b32 v138, v108, v128
	ds_bpermute_b32 v139, v108, v129
	ds_bpermute_b32 v140, v108, v130
	ds_bpermute_b32 v141, v108, v131
	s_waitcnt lgkmcnt(5)
	v_add_f32_e32 v126, v126, v136
	s_waitcnt lgkmcnt(4)
	v_add_f32_e32 v127, v127, v137
	s_waitcnt lgkmcnt(3)
	v_add_f32_e32 v128, v128, v138
	s_waitcnt lgkmcnt(2)
	v_add_f32_e32 v129, v129, v139
	s_waitcnt lgkmcnt(1)
	v_add_f32_e32 v130, v130, v140
	s_waitcnt lgkmcnt(0)
	v_add_f32_e32 v131, v131, v141
	ds_bpermute_b32 v136, v109, v126
	ds_bpermute_b32 v137, v109, v127
	ds_bpermute_b32 v138, v109, v128
	ds_bpermute_b32 v139, v109, v129
	ds_bpermute_b32 v140, v109, v130
	ds_bpermute_b32 v141, v109, v131
	s_waitcnt lgkmcnt(5)
	v_add_f32_e32 v126, v126, v136
	s_waitcnt lgkmcnt(4)
	v_add_f32_e32 v127, v127, v137
	s_waitcnt lgkmcnt(3)
	v_add_f32_e32 v128, v128, v138
	s_waitcnt lgkmcnt(2)
	v_add_f32_e32 v129, v129, v139
	s_waitcnt lgkmcnt(1)
	v_add_f32_e32 v130, v130, v140
	s_waitcnt lgkmcnt(0)
	v_add_f32_e32 v131, v131, v141
	ds_bpermute_b32 v136, v110, v126
	ds_bpermute_b32 v137, v110, v127
	ds_bpermute_b32 v138, v110, v128
	ds_bpermute_b32 v139, v110, v129
	ds_bpermute_b32 v140, v110, v130
	ds_bpermute_b32 v141, v110, v131
	s_waitcnt lgkmcnt(5)
	v_add_f32_e32 v126, v126, v136
	s_waitcnt lgkmcnt(4)
	v_add_f32_e32 v127, v127, v137
	s_waitcnt lgkmcnt(3)
	v_add_f32_e32 v128, v128, v138
	s_waitcnt lgkmcnt(2)
	v_add_f32_e32 v129, v129, v139
	s_waitcnt lgkmcnt(1)
	v_add_f32_e32 v130, v130, v140
	s_waitcnt lgkmcnt(0)
	v_add_f32_e32 v131, v131, v141
	ds_bpermute_b32 v136, v111, v126
	ds_bpermute_b32 v137, v111, v127
	ds_bpermute_b32 v138, v111, v128
	ds_bpermute_b32 v139, v111, v129
	ds_bpermute_b32 v140, v111, v130
	ds_bpermute_b32 v141, v111, v131
	s_waitcnt lgkmcnt(5)
	v_add_f32_e32 v126, v126, v136
	s_waitcnt lgkmcnt(4)
	v_add_f32_e32 v127, v127, v137
	s_waitcnt lgkmcnt(3)
	v_add_f32_e32 v128, v128, v138
	s_waitcnt lgkmcnt(2)
	v_add_f32_e32 v129, v129, v139
	s_waitcnt lgkmcnt(1)
	v_add_f32_e32 v130, v130, v140
	s_waitcnt lgkmcnt(0)
	v_add_f32_e32 v131, v131, v141
	ds_bpermute_b32 v136, v112, v126
	ds_bpermute_b32 v137, v112, v127
	ds_bpermute_b32 v138, v112, v128
	ds_bpermute_b32 v139, v112, v129
	ds_bpermute_b32 v140, v112, v130
	ds_bpermute_b32 v141, v112, v131
	s_waitcnt lgkmcnt(5)
	v_add_f32_e32 v126, v126, v136
	s_waitcnt lgkmcnt(4)
	v_add_f32_e32 v127, v127, v137
	s_waitcnt lgkmcnt(3)
	v_add_f32_e32 v128, v128, v138
	s_waitcnt lgkmcnt(2)
	v_add_f32_e32 v129, v129, v139
	s_waitcnt lgkmcnt(1)
	v_add_f32_e32 v130, v130, v140
	s_waitcnt lgkmcnt(0)
	v_add_f32_e32 v131, v131, v141
	v_fma_f32 v126, v126, s16, v102
	v_fma_f32 v127, v127, s16, v102
	v_fma_f32 v128, v128, s16, v102
	v_fma_f32 v129, v129, s16, v102
	v_fma_f32 v130, v130, s16, v102
	v_fma_f32 v131, v131, s16, v102
	v_rsq_f32_e32 v126, v126
	v_rsq_f32_e32 v127, v127
	v_rsq_f32_e32 v128, v128
	v_rsq_f32_e32 v129, v129
	v_rsq_f32_e32 v130, v130
	v_rsq_f32_e32 v131, v131
	s_waitcnt vmcnt(48)
	s_waitcnt vmcnt(16)
	v_pk_add_f32 v[160:161], v[160:161], 1.0 op_sel_hi:[1,0]
	v_pk_add_f32 v[162:163], v[162:163], 1.0 op_sel_hi:[1,0]
	v_pk_add_f32 v[164:165], v[164:165], 1.0 op_sel_hi:[1,0]
	v_pk_add_f32 v[166:167], v[166:167], 1.0 op_sel_hi:[1,0]
	v_pk_add_f32 v[168:169], v[168:169], 1.0 op_sel_hi:[1,0]
	v_pk_add_f32 v[170:171], v[170:171], 1.0 op_sel_hi:[1,0]
	v_pk_add_f32 v[172:173], v[172:173], 1.0 op_sel_hi:[1,0]
	v_pk_add_f32 v[174:175], v[174:175], 1.0 op_sel_hi:[1,0]
	v_mul_f32_e32 v0, v0, v126
	v_mul_f32_e32 v1, v1, v126
	v_mul_f32_e32 v2, v2, v126
	v_mul_f32_e32 v3, v3, v126
	v_pk_mul_f32 v[0:1], v[0:1], v[144:145]
	v_pk_mul_f32 v[2:3], v[2:3], v[146:147]
	v_pk_fma_f32 v[0:1], v[0:1], v[160:161], v[176:177]
	v_pk_fma_f32 v[2:3], v[2:3], v[162:163], v[178:179]
	v_cvt_pk_bf16_f32 v0, v0, v1
	v_cvt_pk_bf16_f32 v1, v2, v3
	global_store_dwordx2 v96, v[0:1], s[46:47]
	v_mul_f32_e32 v4, v4, v126
	v_mul_f32_e32 v5, v5, v126
	v_mul_f32_e32 v6, v6, v126
	v_mul_f32_e32 v7, v7, v126
	v_pk_mul_f32 v[4:5], v[4:5], v[148:149]
	v_pk_mul_f32 v[6:7], v[6:7], v[150:151]
	v_pk_fma_f32 v[4:5], v[4:5], v[164:165], v[180:181]
	v_pk_fma_f32 v[6:7], v[6:7], v[166:167], v[182:183]
	v_cvt_pk_bf16_f32 v4, v4, v5
	v_cvt_pk_bf16_f32 v5, v6, v7
	global_store_dwordx2 v96, v[4:5], s[46:47] offset:512
	v_mul_f32_e32 v8, v8, v126
	v_mul_f32_e32 v9, v9, v126
	v_mul_f32_e32 v10, v10, v126
	v_mul_f32_e32 v11, v11, v126
	v_pk_mul_f32 v[8:9], v[8:9], v[152:153]
	v_pk_mul_f32 v[10:11], v[10:11], v[154:155]
	v_pk_fma_f32 v[8:9], v[8:9], v[168:169], v[184:185]
	v_pk_fma_f32 v[10:11], v[10:11], v[170:171], v[186:187]
	v_cvt_pk_bf16_f32 v8, v8, v9
	v_cvt_pk_bf16_f32 v9, v10, v11
	global_store_dwordx2 v96, v[8:9], s[46:47] offset:1024
	v_mul_f32_e32 v12, v12, v126
	v_mul_f32_e32 v13, v13, v126
	v_mul_f32_e32 v14, v14, v126
	v_mul_f32_e32 v15, v15, v126
	v_pk_mul_f32 v[12:13], v[12:13], v[156:157]
	v_pk_mul_f32 v[14:15], v[14:15], v[158:159]
	v_pk_fma_f32 v[12:13], v[12:13], v[172:173], v[188:189]
	v_pk_fma_f32 v[14:15], v[14:15], v[174:175], v[190:191]
	v_cvt_pk_bf16_f32 v12, v12, v13
	v_cvt_pk_bf16_f32 v13, v14, v15
	global_store_dwordx2 v96, v[12:13], s[46:47] offset:1536
	s_add_u32 s46, s46, 0x400000
	s_addc_u32 s47, s47, 0
	v_mul_f32_e32 v16, v16, v127
	v_mul_f32_e32 v17, v17, v127
	v_mul_f32_e32 v18, v18, v127
	v_mul_f32_e32 v19, v19, v127
	v_pk_mul_f32 v[16:17], v[16:17], v[144:145]
	v_pk_mul_f32 v[18:19], v[18:19], v[146:147]
	v_pk_fma_f32 v[16:17], v[16:17], v[160:161], v[176:177]
	v_pk_fma_f32 v[18:19], v[18:19], v[162:163], v[178:179]
	v_cvt_pk_bf16_f32 v16, v16, v17
	v_cvt_pk_bf16_f32 v17, v18, v19
	global_store_dwordx2 v96, v[16:17], s[46:47]
	v_mul_f32_e32 v20, v20, v127
	v_mul_f32_e32 v21, v21, v127
	v_mul_f32_e32 v22, v22, v127
	v_mul_f32_e32 v23, v23, v127
	v_pk_mul_f32 v[20:21], v[20:21], v[148:149]
	v_pk_mul_f32 v[22:23], v[22:23], v[150:151]
	v_pk_fma_f32 v[20:21], v[20:21], v[164:165], v[180:181]
	v_pk_fma_f32 v[22:23], v[22:23], v[166:167], v[182:183]
	v_cvt_pk_bf16_f32 v20, v20, v21
	v_cvt_pk_bf16_f32 v21, v22, v23
	global_store_dwordx2 v96, v[20:21], s[46:47] offset:512
	v_mul_f32_e32 v24, v24, v127
	v_mul_f32_e32 v25, v25, v127
	v_mul_f32_e32 v26, v26, v127
	v_mul_f32_e32 v27, v27, v127
	v_pk_mul_f32 v[24:25], v[24:25], v[152:153]
	v_pk_mul_f32 v[26:27], v[26:27], v[154:155]
	v_pk_fma_f32 v[24:25], v[24:25], v[168:169], v[184:185]
	v_pk_fma_f32 v[26:27], v[26:27], v[170:171], v[186:187]
	v_cvt_pk_bf16_f32 v24, v24, v25
	v_cvt_pk_bf16_f32 v25, v26, v27
	global_store_dwordx2 v96, v[24:25], s[46:47] offset:1024
	v_mul_f32_e32 v28, v28, v127
	v_mul_f32_e32 v29, v29, v127
	v_mul_f32_e32 v30, v30, v127
	v_mul_f32_e32 v31, v31, v127
	v_pk_mul_f32 v[28:29], v[28:29], v[156:157]
	v_pk_mul_f32 v[30:31], v[30:31], v[158:159]
	v_pk_fma_f32 v[28:29], v[28:29], v[172:173], v[188:189]
	v_pk_fma_f32 v[30:31], v[30:31], v[174:175], v[190:191]
	v_cvt_pk_bf16_f32 v28, v28, v29
	v_cvt_pk_bf16_f32 v29, v30, v31
	global_store_dwordx2 v96, v[28:29], s[46:47] offset:1536
	s_add_u32 s46, s46, 0x400000
	s_addc_u32 s47, s47, 0
	s_add_u32 s48, s39, 0x9000
	s_addc_u32 s49, s40, 0
	s_add_u32 s50, s48, 0x1000
	s_addc_u32 s51, s49, 0
	global_load_dwordx4 v[160:163], v114, s[50:51]
	global_load_dwordx4 v[164:167], v114, s[50:51] offset:1024
	global_load_dwordx4 v[168:171], v114, s[50:51] offset:2048
	global_load_dwordx4 v[172:175], v114, s[50:51] offset:3072
	global_load_dwordx4 v[176:179], v114, s[48:49]
	global_load_dwordx4 v[180:183], v114, s[48:49] offset:1024
	global_load_dwordx4 v[184:187], v114, s[48:49] offset:2048
	global_load_dwordx4 v[188:191], v114, s[48:49] offset:3072
	s_waitcnt vmcnt(24)
	v_pk_add_f32 v[196:197], v[196:197], 1.0 op_sel_hi:[1,0]
	v_pk_add_f32 v[198:199], v[198:199], 1.0 op_sel_hi:[1,0]
	v_pk_add_f32 v[200:201], v[200:201], 1.0 op_sel_hi:[1,0]
	v_pk_add_f32 v[202:203], v[202:203], 1.0 op_sel_hi:[1,0]
	v_pk_add_f32 v[204:205], v[204:205], 1.0 op_sel_hi:[1,0]
	v_pk_add_f32 v[206:207], v[206:207], 1.0 op_sel_hi:[1,0]
	v_pk_add_f32 v[208:209], v[208:209], 1.0 op_sel_hi:[1,0]
	v_pk_add_f32 v[210:211], v[210:211], 1.0 op_sel_hi:[1,0]
	v_mul_f32_e32 v32, v32, v128
	v_mul_f32_e32 v33, v33, v128
	v_mul_f32_e32 v34, v34, v128
	v_mul_f32_e32 v35, v35, v128
	v_pk_mul_f32 v[32:33], v[32:33], v[144:145]
	v_pk_mul_f32 v[34:35], v[34:35], v[146:147]
	v_pk_fma_f32 v[32:33], v[32:33], v[196:197], v[212:213]
	v_pk_fma_f32 v[34:35], v[34:35], v[198:199], v[214:215]
	v_cvt_pk_bf16_f32 v32, v32, v33
	v_cvt_pk_bf16_f32 v33, v34, v35
	global_store_dwordx2 v96, v[32:33], s[46:47]
	v_mul_f32_e32 v36, v36, v128
	v_mul_f32_e32 v37, v37, v128
	v_mul_f32_e32 v38, v38, v128
	v_mul_f32_e32 v39, v39, v128
	v_pk_mul_f32 v[36:37], v[36:37], v[148:149]
	v_pk_mul_f32 v[38:39], v[38:39], v[150:151]
	v_pk_fma_f32 v[36:37], v[36:37], v[200:201], v[216:217]
	v_pk_fma_f32 v[38:39], v[38:39], v[202:203], v[218:219]
	v_cvt_pk_bf16_f32 v36, v36, v37
	v_cvt_pk_bf16_f32 v37, v38, v39
	global_store_dwordx2 v96, v[36:37], s[46:47] offset:512
	v_mul_f32_e32 v40, v40, v128
	v_mul_f32_e32 v41, v41, v128
	v_mul_f32_e32 v42, v42, v128
	v_mul_f32_e32 v43, v43, v128
	v_pk_mul_f32 v[40:41], v[40:41], v[152:153]
	v_pk_mul_f32 v[42:43], v[42:43], v[154:155]
	v_pk_fma_f32 v[40:41], v[40:41], v[204:205], v[220:221]
	v_pk_fma_f32 v[42:43], v[42:43], v[206:207], v[222:223]
	v_cvt_pk_bf16_f32 v40, v40, v41
	v_cvt_pk_bf16_f32 v41, v42, v43
	global_store_dwordx2 v96, v[40:41], s[46:47] offset:1024
	v_mul_f32_e32 v44, v44, v128
	v_mul_f32_e32 v45, v45, v128
	v_mul_f32_e32 v46, v46, v128
	v_mul_f32_e32 v47, v47, v128
	v_pk_mul_f32 v[44:45], v[44:45], v[156:157]
	v_pk_mul_f32 v[46:47], v[46:47], v[158:159]
	v_pk_fma_f32 v[44:45], v[44:45], v[208:209], v[224:225]
	v_pk_fma_f32 v[46:47], v[46:47], v[210:211], v[226:227]
	v_cvt_pk_bf16_f32 v44, v44, v45
	v_cvt_pk_bf16_f32 v45, v46, v47
	global_store_dwordx2 v96, v[44:45], s[46:47] offset:1536
	s_add_u32 s46, s46, 0x400000
	s_addc_u32 s47, s47, 0
	s_add_u32 s48, s39, 0xc000
	s_addc_u32 s49, s40, 0
	s_add_u32 s50, s48, 0x1000
	s_addc_u32 s51, s49, 0
	global_load_dwordx4 v[196:199], v114, s[50:51]
	global_load_dwordx4 v[200:203], v114, s[50:51] offset:1024
	global_load_dwordx4 v[204:207], v114, s[50:51] offset:2048
	global_load_dwordx4 v[208:211], v114, s[50:51] offset:3072
	global_load_dwordx4 v[212:215], v114, s[48:49]
	global_load_dwordx4 v[216:219], v114, s[48:49] offset:1024
	global_load_dwordx4 v[220:223], v114, s[48:49] offset:2048
	global_load_dwordx4 v[224:227], v114, s[48:49] offset:3072
	s_waitcnt vmcnt(28)
	v_pk_add_f32 v[228:229], v[228:229], 1.0 op_sel_hi:[1,0]
	v_pk_add_f32 v[230:231], v[230:231], 1.0 op_sel_hi:[1,0]
	v_pk_add_f32 v[232:233], v[232:233], 1.0 op_sel_hi:[1,0]
	v_pk_add_f32 v[234:235], v[234:235], 1.0 op_sel_hi:[1,0]
	v_pk_add_f32 v[236:237], v[236:237], 1.0 op_sel_hi:[1,0]
	v_pk_add_f32 v[238:239], v[238:239], 1.0 op_sel_hi:[1,0]
	v_pk_add_f32 v[240:241], v[240:241], 1.0 op_sel_hi:[1,0]
	v_pk_add_f32 v[242:243], v[242:243], 1.0 op_sel_hi:[1,0]
	v_mul_f32_e32 v48, v48, v129
	v_mul_f32_e32 v49, v49, v129
	v_mul_f32_e32 v50, v50, v129
	v_mul_f32_e32 v51, v51, v129
	v_pk_mul_f32 v[48:49], v[48:49], v[144:145]
	v_pk_mul_f32 v[50:51], v[50:51], v[146:147]
	v_pk_fma_f32 v[48:49], v[48:49], v[228:229], v[244:245]
	v_pk_fma_f32 v[50:51], v[50:51], v[230:231], v[246:247]
	v_cvt_pk_bf16_f32 v48, v48, v49
	v_cvt_pk_bf16_f32 v49, v50, v51
	global_store_dwordx2 v96, v[48:49], s[46:47]
	v_mul_f32_e32 v52, v52, v129
	v_mul_f32_e32 v53, v53, v129
	v_mul_f32_e32 v54, v54, v129
	v_mul_f32_e32 v55, v55, v129
	v_pk_mul_f32 v[52:53], v[52:53], v[148:149]
	v_pk_mul_f32 v[54:55], v[54:55], v[150:151]
	v_pk_fma_f32 v[52:53], v[52:53], v[232:233], v[248:249]
	v_pk_fma_f32 v[54:55], v[54:55], v[234:235], v[250:251]
	v_cvt_pk_bf16_f32 v52, v52, v53
	v_cvt_pk_bf16_f32 v53, v54, v55
	global_store_dwordx2 v96, v[52:53], s[46:47] offset:512
	v_mul_f32_e32 v56, v56, v129
	v_mul_f32_e32 v57, v57, v129
	v_mul_f32_e32 v58, v58, v129
	v_mul_f32_e32 v59, v59, v129
	v_pk_mul_f32 v[56:57], v[56:57], v[152:153]
	v_pk_mul_f32 v[58:59], v[58:59], v[154:155]
	v_pk_fma_f32 v[56:57], v[56:57], v[236:237], v[118:119]
	v_pk_fma_f32 v[58:59], v[58:59], v[238:239], v[120:121]
	v_cvt_pk_bf16_f32 v56, v56, v57
	v_cvt_pk_bf16_f32 v57, v58, v59
	global_store_dwordx2 v96, v[56:57], s[46:47] offset:1024
	v_mul_f32_e32 v60, v60, v129
	v_mul_f32_e32 v61, v61, v129
	v_mul_f32_e32 v62, v62, v129
	v_mul_f32_e32 v63, v63, v129
	v_pk_mul_f32 v[60:61], v[60:61], v[156:157]
	v_pk_mul_f32 v[62:63], v[62:63], v[158:159]
	v_pk_fma_f32 v[60:61], v[60:61], v[240:241], v[122:123]
	v_pk_fma_f32 v[62:63], v[62:63], v[242:243], v[124:125]
	v_cvt_pk_bf16_f32 v60, v60, v61
	v_cvt_pk_bf16_f32 v61, v62, v63
	global_store_dwordx2 v96, v[60:61], s[46:47] offset:1536
	s_add_u32 s46, s46, 0x400000
	s_addc_u32 s47, s47, 0
	s_waitcnt vmcnt(16)
	v_pk_add_f32 v[160:161], v[160:161], 1.0 op_sel_hi:[1,0]
	v_pk_add_f32 v[162:163], v[162:163], 1.0 op_sel_hi:[1,0]
	v_pk_add_f32 v[164:165], v[164:165], 1.0 op_sel_hi:[1,0]
	v_pk_add_f32 v[166:167], v[166:167], 1.0 op_sel_hi:[1,0]
	v_pk_add_f32 v[168:169], v[168:169], 1.0 op_sel_hi:[1,0]
	v_pk_add_f32 v[170:171], v[170:171], 1.0 op_sel_hi:[1,0]
	v_pk_add_f32 v[172:173], v[172:173], 1.0 op_sel_hi:[1,0]
	v_pk_add_f32 v[174:175], v[174:175], 1.0 op_sel_hi:[1,0]
	v_mul_f32_e32 v64, v64, v130
	v_mul_f32_e32 v65, v65, v130
	v_mul_f32_e32 v66, v66, v130
	v_mul_f32_e32 v67, v67, v130
	v_pk_mul_f32 v[64:65], v[64:65], v[144:145]
	v_pk_mul_f32 v[66:67], v[66:67], v[146:147]
	v_pk_fma_f32 v[64:65], v[64:65], v[160:161], v[176:177]
	v_pk_fma_f32 v[66:67], v[66:67], v[162:163], v[178:179]
	v_cvt_pk_bf16_f32 v64, v64, v65
	v_cvt_pk_bf16_f32 v65, v66, v67
	global_store_dwordx2 v96, v[64:65], s[46:47]
	v_mul_f32_e32 v68, v68, v130
	v_mul_f32_e32 v69, v69, v130
	v_mul_f32_e32 v70, v70, v130
	v_mul_f32_e32 v71, v71, v130
	v_pk_mul_f32 v[68:69], v[68:69], v[148:149]
	v_pk_mul_f32 v[70:71], v[70:71], v[150:151]
	v_pk_fma_f32 v[68:69], v[68:69], v[164:165], v[180:181]
	v_pk_fma_f32 v[70:71], v[70:71], v[166:167], v[182:183]
	v_cvt_pk_bf16_f32 v68, v68, v69
	v_cvt_pk_bf16_f32 v69, v70, v71
	global_store_dwordx2 v96, v[68:69], s[46:47] offset:512
	v_mul_f32_e32 v72, v72, v130
	v_mul_f32_e32 v73, v73, v130
	v_mul_f32_e32 v74, v74, v130
	v_mul_f32_e32 v75, v75, v130
	v_pk_mul_f32 v[72:73], v[72:73], v[152:153]
	v_pk_mul_f32 v[74:75], v[74:75], v[154:155]
	v_pk_fma_f32 v[72:73], v[72:73], v[168:169], v[184:185]
	v_pk_fma_f32 v[74:75], v[74:75], v[170:171], v[186:187]
	v_cvt_pk_bf16_f32 v72, v72, v73
	v_cvt_pk_bf16_f32 v73, v74, v75
	global_store_dwordx2 v96, v[72:73], s[46:47] offset:1024
	v_mul_f32_e32 v76, v76, v130
	v_mul_f32_e32 v77, v77, v130
	v_mul_f32_e32 v78, v78, v130
	v_mul_f32_e32 v79, v79, v130
	v_pk_mul_f32 v[76:77], v[76:77], v[156:157]
	v_pk_mul_f32 v[78:79], v[78:79], v[158:159]
	v_pk_fma_f32 v[76:77], v[76:77], v[172:173], v[188:189]
	v_pk_fma_f32 v[78:79], v[78:79], v[174:175], v[190:191]
	v_cvt_pk_bf16_f32 v76, v76, v77
	v_cvt_pk_bf16_f32 v77, v78, v79
	global_store_dwordx2 v96, v[76:77], s[46:47] offset:1536
	s_add_u32 s46, s46, 0x400000
	s_addc_u32 s47, s47, 0
	s_waitcnt vmcnt(8)
	v_pk_add_f32 v[196:197], v[196:197], 1.0 op_sel_hi:[1,0]
	v_pk_add_f32 v[198:199], v[198:199], 1.0 op_sel_hi:[1,0]
	v_pk_add_f32 v[200:201], v[200:201], 1.0 op_sel_hi:[1,0]
	v_pk_add_f32 v[202:203], v[202:203], 1.0 op_sel_hi:[1,0]
	v_pk_add_f32 v[204:205], v[204:205], 1.0 op_sel_hi:[1,0]
	v_pk_add_f32 v[206:207], v[206:207], 1.0 op_sel_hi:[1,0]
	v_pk_add_f32 v[208:209], v[208:209], 1.0 op_sel_hi:[1,0]
	v_pk_add_f32 v[210:211], v[210:211], 1.0 op_sel_hi:[1,0]
	v_mul_f32_e32 v80, v80, v131
	v_mul_f32_e32 v81, v81, v131
	v_mul_f32_e32 v82, v82, v131
	v_mul_f32_e32 v83, v83, v131
	v_pk_mul_f32 v[80:81], v[80:81], v[144:145]
	v_pk_mul_f32 v[82:83], v[82:83], v[146:147]
	v_pk_fma_f32 v[80:81], v[80:81], v[196:197], v[212:213]
	v_pk_fma_f32 v[82:83], v[82:83], v[198:199], v[214:215]
	v_cvt_pk_bf16_f32 v80, v80, v81
	v_cvt_pk_bf16_f32 v81, v82, v83
	global_store_dwordx2 v96, v[80:81], s[46:47]
	v_mul_f32_e32 v84, v84, v131
	v_mul_f32_e32 v85, v85, v131
	v_mul_f32_e32 v86, v86, v131
	v_mul_f32_e32 v87, v87, v131
	v_pk_mul_f32 v[84:85], v[84:85], v[148:149]
	v_pk_mul_f32 v[86:87], v[86:87], v[150:151]
	v_pk_fma_f32 v[84:85], v[84:85], v[200:201], v[216:217]
	v_pk_fma_f32 v[86:87], v[86:87], v[202:203], v[218:219]
	v_cvt_pk_bf16_f32 v84, v84, v85
	v_cvt_pk_bf16_f32 v85, v86, v87
	global_store_dwordx2 v96, v[84:85], s[46:47] offset:512
	v_mul_f32_e32 v88, v88, v131
	v_mul_f32_e32 v89, v89, v131
	v_mul_f32_e32 v90, v90, v131
	v_mul_f32_e32 v91, v91, v131
	v_pk_mul_f32 v[88:89], v[88:89], v[152:153]
	v_pk_mul_f32 v[90:91], v[90:91], v[154:155]
	v_pk_fma_f32 v[88:89], v[88:89], v[204:205], v[220:221]
	v_pk_fma_f32 v[90:91], v[90:91], v[206:207], v[222:223]
	v_cvt_pk_bf16_f32 v88, v88, v89
	v_cvt_pk_bf16_f32 v89, v90, v91
	global_store_dwordx2 v96, v[88:89], s[46:47] offset:1024
	v_mul_f32_e32 v92, v92, v131
	v_mul_f32_e32 v93, v93, v131
	v_mul_f32_e32 v94, v94, v131
	v_mul_f32_e32 v95, v95, v131
	v_pk_mul_f32 v[92:93], v[92:93], v[156:157]
	v_pk_mul_f32 v[94:95], v[94:95], v[158:159]
	v_pk_fma_f32 v[92:93], v[92:93], v[208:209], v[224:225]
	v_pk_fma_f32 v[94:95], v[94:95], v[210:211], v[226:227]
	v_cvt_pk_bf16_f32 v92, v92, v93
	v_cvt_pk_bf16_f32 v93, v94, v95
	global_store_dwordx2 v96, v[92:93], s[46:47] offset:1536

.LBB0_212:
	s_or_b64 exec, exec, s[8:9]
	v_cvt_f32_u32_e32 v4, v2
	s_waitcnt vmcnt(0)
	v_readfirstlane_b32 s6, v3
	v_sub_u32_e32 v3, 0, v2
	v_rcp_iflag_f32_e32 v4, v4
	v_add_u32_e32 v5, s6, v1
	v_mul_f32_e32 v4, 0x4f7ffffe, v4
	v_cvt_u32_f32_e32 v4, v4
	v_mul_lo_u32 v1, v3, v4
	v_mul_hi_u32 v1, v4, v1
	v_add_u32_e32 v1, v4, v1
	v_mul_hi_u32 v1, v5, v1
	v_mul_lo_u32 v3, v1, v2
	v_sub_u32_e32 v3, v5, v3
	v_add_u32_e32 v4, 1, v1
	v_cmp_ge_u32_e32 vcc, v3, v2
	s_nop 1
	v_cndmask_b32_e32 v1, v1, v4, vcc
	v_sub_u32_e32 v4, v3, v2
	v_cndmask_b32_e32 v3, v3, v4, vcc
	v_add_u32_e32 v4, 1, v1
	v_cmp_ge_u32_e32 vcc, v3, v2
	v_add_u32_e32 v3, 1, v5
	s_nop 0
	v_cndmask_b32_e32 v1, v1, v4, vcc
	v_mul_lo_u32 v4, v2, v1
	v_add_u32_e32 v2, v4, v2
	v_cmp_ne_u32_e32 vcc, v3, v2
	s_and_saveexec_b64 s[6:7], vcc
	s_xor_b64 s[6:7], exec, s[6:7]
	s_cbranch_execz .LBB0_226
	s_waitcnt lgkmcnt(0)
	s_add_u32 s14, s92, 0xf201500
	s_addc_u32 s15, s93, 0
	v_mov_b32_e32 v0, 0
	global_load_dword v0, v0, s[14:15] sc1
	s_waitcnt vmcnt(0)
	v_cmp_eq_u32_e32 vcc, v0, v1
	s_and_saveexec_b64 s[8:9], vcc
	s_cbranch_execz .LBB0_225
	s_add_u32 s12, s92, 0xf1fe200
	s_addc_u32 s13, s93, 0
	s_mov_b32 s26, 1
	s_mov_b64 s[16:17], 0
	v_mov_b32_e32 v0, 0
	s_branch .LBB0_216

.LBB0_301:
	s_or_b64 exec, exec, s[10:11]
	v_cvt_f32_u32_e32 v4, v2
	s_waitcnt vmcnt(0)
	v_readfirstlane_b32 s4, v3
	v_sub_u32_e32 v3, 0, v2
	v_rcp_iflag_f32_e32 v4, v4
	v_add_u32_e32 v5, s4, v1
	v_mul_f32_e32 v4, 0x4f7ffffe, v4
	v_cvt_u32_f32_e32 v4, v4
	v_mul_lo_u32 v1, v3, v4
	v_mul_hi_u32 v1, v4, v1
	v_add_u32_e32 v1, v4, v1
	v_mul_hi_u32 v1, v5, v1
	v_mul_lo_u32 v3, v1, v2
	v_sub_u32_e32 v3, v5, v3
	v_add_u32_e32 v4, 1, v1
	v_cmp_ge_u32_e32 vcc, v3, v2
	s_nop 1
	v_cndmask_b32_e32 v1, v1, v4, vcc
	v_sub_u32_e32 v4, v3, v2
	v_cndmask_b32_e32 v3, v3, v4, vcc
	v_add_u32_e32 v4, 1, v1
	v_cmp_ge_u32_e32 vcc, v3, v2
	v_add_u32_e32 v3, 1, v5
	s_nop 0
	v_cndmask_b32_e32 v1, v1, v4, vcc
	v_mul_lo_u32 v4, v2, v1
	v_add_u32_e32 v2, v4, v2
	v_cmp_ne_u32_e32 vcc, v3, v2
	s_and_saveexec_b64 s[4:5], vcc
	s_xor_b64 s[10:11], exec, s[4:5]
	s_cbranch_execz .LBB0_315
	v_readlane_b32 s4, v254, 16
	v_readlane_b32 s5, v254, 17
	s_waitcnt lgkmcnt(0)
	s_nop 3
	global_load_dword v0, v193, s[4:5] sc1
	s_waitcnt vmcnt(0)
	v_cmp_eq_u32_e32 vcc, v0, v1
	s_and_saveexec_b64 s[16:17], vcc
	s_cbranch_execz .LBB0_314
	s_mov_b32 s4, 1
	s_mov_b64 s[18:19], 0
	s_branch .LBB0_305

.LBB0_307:
	v_readlane_b32 s36, v254, 16
	v_readlane_b32 s37, v254, 17
	s_add_i32 s4, s4, 1
	s_mov_b64 s[38:39], -1
	s_nop 2
	global_load_dword v0, v193, s[36:37] sc1
	s_waitcnt vmcnt(0)
	v_cmp_ne_u32_e32 vcc, v0, v1
	s_orn2_b64 s[36:37], vcc, exec
	s_branch .LBB0_304

.LBB0_502:
	s_or_b64 exec, exec, s[10:11]
	v_cvt_f32_u32_e32 v4, v2
	s_waitcnt vmcnt(0)
	v_readfirstlane_b32 s5, v3
	v_sub_u32_e32 v3, 0, v2
	v_rcp_iflag_f32_e32 v4, v4
	v_add_u32_e32 v5, s5, v1
	v_mul_f32_e32 v4, 0x4f7ffffe, v4
	v_cvt_u32_f32_e32 v4, v4
	v_mul_lo_u32 v1, v3, v4
	v_mul_hi_u32 v1, v4, v1
	v_add_u32_e32 v1, v4, v1
	v_mul_hi_u32 v1, v5, v1
	v_mul_lo_u32 v3, v1, v2
	v_sub_u32_e32 v3, v5, v3
	v_add_u32_e32 v4, 1, v1
	v_cmp_ge_u32_e32 vcc, v3, v2
	s_nop 1
	v_cndmask_b32_e32 v1, v1, v4, vcc
	v_sub_u32_e32 v4, v3, v2
	v_cndmask_b32_e32 v3, v3, v4, vcc
	v_add_u32_e32 v4, 1, v1
	v_cmp_ge_u32_e32 vcc, v3, v2
	v_add_u32_e32 v3, 1, v5
	s_nop 0
	v_cndmask_b32_e32 v1, v1, v4, vcc
	v_mul_lo_u32 v4, v2, v1
	v_add_u32_e32 v2, v4, v2
	v_cmp_ne_u32_e32 vcc, v3, v2
	s_and_saveexec_b64 s[10:11], vcc
	s_xor_b64 s[10:11], exec, s[10:11]
	s_cbranch_execz .LBB0_516
	v_readlane_b32 s16, v254, 16
	v_readlane_b32 s17, v254, 17
	s_waitcnt lgkmcnt(0)
	s_nop 3
	global_load_dword v0, v193, s[16:17] sc1
	s_waitcnt vmcnt(0)
	v_cmp_eq_u32_e32 vcc, v0, v1
	s_and_saveexec_b64 s[16:17], vcc
	s_cbranch_execz .LBB0_515
	s_mov_b32 s5, 1
	s_mov_b64 s[18:19], 0
	s_branch .LBB0_506

.LBB0_508:
	v_readlane_b32 s36, v254, 16
	v_readlane_b32 s37, v254, 17
	s_add_i32 s5, s5, 1
	s_mov_b64 s[38:39], -1
	s_nop 2
	global_load_dword v0, v193, s[36:37] sc1
	s_waitcnt vmcnt(0)
	v_cmp_ne_u32_e32 vcc, v0, v1
	s_orn2_b64 s[36:37], vcc, exec
	s_branch .LBB0_505

.LBB0_1614:
	v_readlane_b32 s36, v254, 16
	v_readlane_b32 s37, v254, 17
	s_add_i32 s5, s5, 1
	s_mov_b64 s[40:41], -1
	s_nop 2
	global_load_dword v0, v193, s[36:37] sc1
	s_waitcnt vmcnt(0)
	v_cmp_ne_u32_e32 vcc, v0, v1
	s_orn2_b64 s[36:37], vcc, exec
	s_branch .LBB0_1611

.LBB0_1805:
	v_readlane_b32 s30, v254, 16
	v_readlane_b32 s31, v254, 17
	s_add_i32 s4, s4, 1
	s_mov_b64 s[36:37], -1
	s_nop 2
	global_load_dword v0, v193, s[30:31] sc1
	s_waitcnt vmcnt(0)
	v_cmp_ne_u32_e32 vcc, v0, v1
	s_orn2_b64 s[30:31], vcc, exec
	s_branch .LBB0_1802
